# k-loop back-edge rotation (7.11): loop-back barrier is the loop head, exit test and branch run before it
# speedup vs baseline: 1.0043x; 1.0025x over previous
; #define TIDX (tid_launder())
; #define G_STORE(ST, S, unused) do { char* d_ = smem + (ST) * STAGE; \
;     *(uint4*)(d_ + alo[0]) = S##a0; *(uint4*)(d_ + alo[1]) = S##a1; *(uint4*)(d_ + alo[2]) = S##a2; *(uint4*)(d_ + alo[3]) = S##a3; \
;     *(uint4*)(d_ + blo[0]) = S##b0; *(uint4*)(d_ + blo[1]) = S##b1; \
;     if (NBCH == 4) { *(uint4*)(d_ + blo[NBCH - 2]) = S##b2; *(uint4*)(d_ + blo[NBCH - 1]) = S##b3; } } while (0)
; template <int NJ, class RowA>
; DI void gemm_main(f32x16 (&acc)[2][NJ], const bf16_t* __restrict__ A, RowA rowA, size_t kstrideA, int m0, int Mmax,
;                   const bf16_t* __restrict__ Bt, size_t ldb, int n0, int nk, char* smem) {
;     ...
;   const int tid = TIDX, lane = tid & 63, wid = tid >> 6, wm = wid >> 1, wn = wid & 1;
;   const int r = lane & 31, hh = lane >> 5;
;   const bf16_t* ap[4]; const bf16_t* bp[NBCH]; int alo[4], blo[NBCH];
; #pragma unroll
;   for (int i = 0; i < 4; ++i) {
;     const int c = tid + 256 * i, row = c >> 3, kc = c & 7;
;     int m = m0 + row; m = m < Mmax ? m : Mmax - 1;
;     ap[i] = A + rowA(m) + kc * 8; alo[i] = row * 144 + kc * 16;
;   }
; #pragma unroll
;   for (int i = 0; i < NBCH; ++i) {
;     const int c = tid + 256 * i, row = c >> 3, kc = c & 7;
;     bp[i] = Bt + (size_t)(n0 + row) * ldb + kc * 8; blo[i] = 128 * 144 + row * 144 + kc * 16;
;   }
; #pragma unroll
;   for (int i = 0; i < 2; ++i)
; #pragma unroll
;     for (int j = 0; j < NJ; ++j)
; #pragma unroll
;       for (int e = 0; e < 16; ++e) acc[i][j][e] = 0.f;
;   uint4 x0a0, x0a1, x0a2, x0a3, x0b0, x0b1, x0b2, x0b3, x1a0, x1a1, x1a2, x1a3, x1b0, x1b1, x1b2, x1b3;
;   x0b2 = x0b3 = x1b2 = x1b3 = make_uint4(0, 0, 0, 0);
;     ...
;   __syncthreads();
;   G_LOAD(x0, 0, 0);
;   G_LOAD(x1, 0, 1);
;   G_STORE(0, x0, 0);
;   __syncthreads();
; #pragma unroll 1
;   for (int kt = 0; kt < nk; kt += 2) {
.LBB0_11:
	v_readlane_b32 s1, v251, 4
	s_add_i32 s1, s0, s1
	s_lshl_b32 s1, s1, 4
	v_mov_b32_e32 v34, v230
	s_and_b32 s1, s1, 0x7f80
	v_readlane_b32 s4, v250, 50
	v_ashrrev_i32_e32 v35, 3, v34
	v_add_u32_e32 v4, s1, v35
	v_lshlrev_b32_e32 v0, 4, v34
	v_min_i32_e32 v4, 0x7fff, v4
	v_and_b32_e32 v0, 0x70, v0
	v_readlane_b32 s5, v250, 51
	v_ashrrev_i32_e32 v5, 31, v4
	v_lshlrev_b64 v[4:5], 11, v[4:5]
	v_lshl_add_u64 v[2:3], s[4:5], 0, v[0:1]
	v_lshl_add_u64 v[122:123], v[2:3], 0, v[4:5]
	v_add_u32_e32 v4, 0x100, v34
	v_ashrrev_i32_e32 v36, 3, v4
	v_add_u32_e32 v4, s1, v36
	v_min_i32_e32 v4, 0x7fff, v4
	v_ashrrev_i32_e32 v5, 31, v4
	v_lshlrev_b64 v[4:5], 11, v[4:5]
	v_lshl_add_u64 v[124:125], v[2:3], 0, v[4:5]
	v_add_u32_e32 v4, 0x200, v34
	v_ashrrev_i32_e32 v37, 3, v4
	v_add_u32_e32 v4, s1, v37
	v_min_i32_e32 v4, 0x7fff, v4
	v_ashrrev_i32_e32 v5, 31, v4
	v_lshlrev_b64 v[4:5], 11, v[4:5]
	v_lshl_add_u64 v[126:127], v[2:3], 0, v[4:5]
	v_add_u32_e32 v4, 0x300, v34
	v_ashrrev_i32_e32 v38, 3, v4
	v_add_u32_e32 v4, s1, v38
	v_min_i32_e32 v4, 0x7fff, v4
	s_lshl_b32 s2, s0, 7
	v_ashrrev_i32_e32 v5, 31, v4
	s_and_b32 s2, s2, 0x380
	v_lshlrev_b64 v[4:5], 11, v[4:5]
	v_lshl_add_u64 v[128:129], v[2:3], 0, v[4:5]
	v_readlane_b32 s16, v252, 57
	v_add_u32_e32 v4, s2, v35
	v_readlane_b32 s18, v252, 59
	v_readlane_b32 s19, v252, 60
	v_ashrrev_i32_e32 v5, 31, v4
	v_lshlrev_b64 v[4:5], 11, v[4:5]
	v_lshl_add_u64 v[2:3], s[18:19], 0, v[0:1]
	v_lshl_add_u64 v[130:131], v[2:3], 0, v[4:5]
	v_add_u32_e32 v4, s2, v36
	v_ashrrev_i32_e32 v5, 31, v4
	v_lshlrev_b64 v[4:5], 11, v[4:5]
	v_lshl_add_u64 v[132:133], v[2:3], 0, v[4:5]
	v_add_u32_e32 v4, s2, v37
	v_ashrrev_i32_e32 v5, 31, v4
	v_lshlrev_b64 v[4:5], 11, v[4:5]
	v_lshl_add_u64 v[134:135], v[2:3], 0, v[4:5]
	v_add_u32_e32 v4, s2, v38
	v_ashrrev_i32_e32 v5, 31, v4
	v_lshlrev_b64 v[4:5], 11, v[4:5]
	v_lshl_add_u64 v[136:137], v[2:3], 0, v[4:5]
	s_barrier
	global_load_dwordx4 v[2:5], v[122:123], off
	global_load_dwordx4 v[6:9], v[124:125], off
	global_load_dwordx4 v[10:13], v[126:127], off
	global_load_dwordx4 v[14:17], v[128:129], off
	global_load_dwordx4 v[18:21], v[130:131], off
	global_load_dwordx4 v[22:25], v[132:133], off
	global_load_dwordx4 v[26:29], v[134:135], off
	global_load_dwordx4 v[30:33], v[136:137], off
	global_load_dwordx4 v[74:77], v[130:131], off offset:128
	global_load_dwordx4 v[66:69], v[134:135], off offset:128
	global_load_dwordx4 v[70:73], v[136:137], off offset:128
	global_load_dwordx4 v[78:81], v[122:123], off offset:128
	global_load_dwordx4 v[82:85], v[132:133], off offset:128
	global_load_dwordx4 v[86:89], v[124:125], off offset:128
	global_load_dwordx4 v[90:93], v[126:127], off offset:128
	global_load_dwordx4 v[94:97], v[128:129], off offset:128
	v_and_b32_e32 v39, 31, v34
	v_mad_u64_u32 v[138:139], s[4:5], v35, s76, v[0:1]
	v_mad_u64_u32 v[140:141], s[4:5], v36, s76, v[0:1]
	v_mad_u64_u32 v[142:143], s[4:5], v37, s76, v[0:1]
	v_mad_u64_u32 v[144:145], s[4:5], v38, s76, v[0:1]
	v_lshrrev_b32_e32 v0, 1, v34
	s_mov_b32 s3, -2
	v_readlane_b32 s6, v250, 52
	v_readlane_b32 s7, v250, 53
	v_readlane_b32 s17, v252, 58
	v_readlane_b32 s20, v252, 61
	v_readlane_b32 s21, v252, 62
	v_readlane_b32 s22, v252, 63
	v_readlane_b32 s23, v253, 0
	v_readlane_b32 s24, v253, 1
	v_readlane_b32 s25, v253, 2
	v_readlane_b32 s26, v253, 3
	v_readlane_b32 s27, v253, 4
	v_readlane_b32 s28, v253, 5
	v_readlane_b32 s29, v253, 6
	v_readlane_b32 s30, v253, 7
	v_readlane_b32 s31, v253, 8
	s_waitcnt vmcnt(15)
	ds_write_b128 v138, v[2:5]
	s_waitcnt vmcnt(14)
	ds_write_b128 v140, v[6:9]
	s_waitcnt vmcnt(13)
	ds_write_b128 v142, v[10:13]
	s_waitcnt vmcnt(12)
	ds_write_b128 v144, v[14:17]
	s_waitcnt vmcnt(11)
	ds_write_b128 v138, v[18:21] offset:18432
	s_waitcnt vmcnt(10)
	ds_write_b128 v140, v[22:25] offset:18432
	s_waitcnt vmcnt(9)
	ds_write_b128 v142, v[26:29] offset:18432
	s_waitcnt vmcnt(8)
	ds_write_b128 v144, v[30:33] offset:18432
	v_and_or_b32 v2, v0, s47, v39
	v_and_b32_e32 v3, 16, v0
	v_and_b32_e32 v0, 0x5f, v34
	v_mul_lo_u32 v4, v2, s76
	v_mul_u32_u24_e32 v5, 0x90, v0
	v_mov_b32_e32 v2, 0
	v_add_u32_e32 v0, v3, v4
	v_add_u32_e32 v139, v3, v5
	v_mov_b32_e32 v3, v2
	v_mov_b32_e32 v4, v2
	v_mov_b32_e32 v5, v2
	v_mov_b32_e32 v6, v2
	v_mov_b32_e32 v7, v2
	v_mov_b32_e32 v8, v2
	v_mov_b32_e32 v9, v2
	v_mov_b32_e32 v10, v2
	v_mov_b32_e32 v11, v2
	v_mov_b32_e32 v12, v2
	v_mov_b32_e32 v13, v2
	v_mov_b32_e32 v14, v2
	v_mov_b32_e32 v15, v2
	v_mov_b32_e32 v16, v2
	v_mov_b32_e32 v17, v2
	v_mov_b32_e32 v18, v2
	v_mov_b32_e32 v19, v2
	v_mov_b32_e32 v20, v2
	v_mov_b32_e32 v21, v2
	v_mov_b32_e32 v22, v2
	v_mov_b32_e32 v23, v2
	v_mov_b32_e32 v24, v2
	v_mov_b32_e32 v25, v2
	v_mov_b32_e32 v26, v2
	v_mov_b32_e32 v27, v2
	v_mov_b32_e32 v28, v2
	v_mov_b32_e32 v29, v2
	v_mov_b32_e32 v30, v2
	v_mov_b32_e32 v31, v2
	v_mov_b32_e32 v32, v2
	v_mov_b32_e32 v33, v2
	v_mov_b32_e32 v34, v2
	v_mov_b32_e32 v35, v2
	v_mov_b32_e32 v36, v2
	v_mov_b32_e32 v37, v2
	v_mov_b32_e32 v38, v2
	v_mov_b32_e32 v39, v2
	v_mov_b32_e32 v40, v2
	v_mov_b32_e32 v41, v2
	v_mov_b32_e32 v42, v2
	v_mov_b32_e32 v43, v2
	v_mov_b32_e32 v44, v2
	v_mov_b32_e32 v45, v2
	v_mov_b32_e32 v46, v2
	v_mov_b32_e32 v47, v2
	v_mov_b32_e32 v48, v2
	v_mov_b32_e32 v49, v2
	v_mov_b32_e32 v50, v2
	v_mov_b32_e32 v51, v2
	v_mov_b32_e32 v52, v2
	v_mov_b32_e32 v53, v2
	v_mov_b32_e32 v54, v2
	v_mov_b32_e32 v55, v2
	v_mov_b32_e32 v56, v2
	v_mov_b32_e32 v57, v2
	v_mov_b32_e32 v58, v2
	v_mov_b32_e32 v59, v2
	v_mov_b32_e32 v60, v2
	v_mov_b32_e32 v61, v2
	v_mov_b32_e32 v62, v2
	v_mov_b32_e32 v63, v2
	v_mov_b32_e32 v64, v2
	v_mov_b32_e32 v65, v2
	s_waitcnt lgkmcnt(0)
.LBB0_12:
	s_cmp_lt_i32 s3, 12
	s_cbranch_scc0 .Lrot_exit_12
; #define G_STORE(ST, S, unused) do { char* d_ = smem + (ST) * STAGE; \
;     *(uint4*)(d_ + alo[0]) = S##a0; *(uint4*)(d_ + alo[1]) = S##a1; *(uint4*)(d_ + alo[2]) = S##a2; *(uint4*)(d_ + alo[3]) = S##a3; \
;     *(uint4*)(d_ + blo[0]) = S##b0; *(uint4*)(d_ + blo[1]) = S##b1; \
;     if (NBCH == 4) { *(uint4*)(d_ + blo[NBCH - 2]) = S##b2; *(uint4*)(d_ + blo[NBCH - 1]) = S##b3; } } while (0)
; template <int NJ, class RowA>
; DI void gemm_main(f32x16 (&acc)[2][NJ], const bf16_t* __restrict__ A, RowA rowA, size_t kstrideA, int m0, int Mmax,
;                   const bf16_t* __restrict__ Bt, size_t ldb, int n0, int nk, char* smem) {
;     ...
; #pragma unroll 1
;   for (int kt = 0; kt < nk; kt += 2) {
;     G_LOAD(x0, 0, (kt + 2 < nk ? kt + 2 : nk - 1));
;     G_COMPUTE(0);
;     G_STORE(1, x1, 0);
;     __syncthreads();
;     G_LOAD(x1, 0, (kt + 3 < nk ? kt + 3 : nk - 1));
;     G_COMPUTE(1);
;     G_STORE(0, x0, 0);
;     __syncthreads();
;   }
.Lrot_body_12:
	s_barrier
	ds_read_b128 v[166:169], v0
	ds_read_b128 v[170:173], v139 offset:18432
	ds_read_b128 v[174:177], v139 offset:23040
	ds_read_b128 v[178:181], v0 offset:4608
	s_add_i32 s4, s3, 4
	s_min_u32 s4, s4, 15
	s_lshl_b32 s14, s4, 7
	v_lshl_add_u64 v[98:99], v[122:123], 0, s[14:15]
	v_lshl_add_u64 v[102:103], v[124:125], 0, s[14:15]
	v_lshl_add_u64 v[106:107], v[126:127], 0, s[14:15]
	v_lshl_add_u64 v[110:111], v[128:129], 0, s[14:15]
	v_lshl_add_u64 v[114:115], v[130:131], 0, s[14:15]
	v_lshl_add_u64 v[118:119], v[132:133], 0, s[14:15]
	s_add_i32 s3, s3, 2
	v_lshl_add_u64 v[158:159], v[134:135], 0, s[14:15]
	v_lshl_add_u64 v[160:161], v[136:137], 0, s[14:15]
	s_setprio 1
	ds_read_b128 v[182:185], v0 offset:32
	ds_read_b128 v[186:189], v139 offset:18464
	ds_read_b128 v[190:193], v139 offset:23072
	ds_read_b128 v[194:197], v0 offset:4640
	s_waitcnt lgkmcnt(4)
	v_mfma_f32_32x32x16_bf16 v[50:65], v[166:169], v[170:173], v[50:65]
	global_load_dwordx4 v[98:101], v[98:99], off
	v_mfma_f32_32x32x16_bf16 v[34:49], v[166:169], v[174:177], v[34:49]
	global_load_dwordx4 v[102:105], v[102:103], off
	v_mfma_f32_32x32x16_bf16 v[18:33], v[178:181], v[170:173], v[18:33]
	global_load_dwordx4 v[106:109], v[106:107], off
	v_mfma_f32_32x32x16_bf16 v[2:17], v[178:181], v[174:177], v[2:17]
	global_load_dwordx4 v[110:113], v[110:111], off
	ds_read_b128 v[166:169], v0 offset:64
	ds_read_b128 v[170:173], v139 offset:18496
	ds_read_b128 v[174:177], v139 offset:23104
	ds_read_b128 v[178:181], v0 offset:4672
	s_waitcnt lgkmcnt(4)
	v_mfma_f32_32x32x16_bf16 v[50:65], v[182:185], v[186:189], v[50:65]
	global_load_dwordx4 v[114:117], v[114:115], off
	s_waitcnt vmcnt(5)
	ds_write_b128 v138, v[78:81] offset:36864
	v_mfma_f32_32x32x16_bf16 v[34:49], v[182:185], v[190:193], v[34:49]
	global_load_dwordx4 v[118:121], v[118:119], off
	ds_write_b128 v140, v[86:89] offset:36864
	v_mfma_f32_32x32x16_bf16 v[18:33], v[194:197], v[186:189], v[18:33]
	global_load_dwordx4 v[146:149], v[160:161], off
	ds_write_b128 v142, v[90:93] offset:36864
	v_mfma_f32_32x32x16_bf16 v[2:17], v[194:197], v[190:193], v[2:17]
	global_load_dwordx4 v[150:153], v[158:159], off
	ds_write_b128 v144, v[94:97] offset:36864
	ds_read_b128 v[182:185], v0 offset:96
	ds_read_b128 v[186:189], v139 offset:18528
	ds_read_b128 v[190:193], v139 offset:23136
	ds_read_b128 v[194:197], v0 offset:4704
	s_waitcnt lgkmcnt(8)
	v_mfma_f32_32x32x16_bf16 v[50:65], v[166:169], v[170:173], v[50:65]
	ds_write_b128 v138, v[74:77] offset:55296
	v_mfma_f32_32x32x16_bf16 v[34:49], v[166:169], v[174:177], v[34:49]
	ds_write_b128 v140, v[82:85] offset:55296
	v_mfma_f32_32x32x16_bf16 v[18:33], v[178:181], v[170:173], v[18:33]
	ds_write_b128 v142, v[66:69] offset:55296
	v_mfma_f32_32x32x16_bf16 v[2:17], v[178:181], v[174:177], v[2:17]
	ds_write_b128 v144, v[70:73] offset:55296
	s_waitcnt lgkmcnt(4)
	v_mfma_f32_32x32x16_bf16 v[50:65], v[182:185], v[186:189], v[50:65]
	v_mfma_f32_32x32x16_bf16 v[34:49], v[182:185], v[190:193], v[34:49]
	v_mfma_f32_32x32x16_bf16 v[18:33], v[194:197], v[186:189], v[18:33]
	v_mfma_f32_32x32x16_bf16 v[2:17], v[194:197], v[190:193], v[2:17]
	s_setprio 0
	s_min_u32 s4, s3, 12
	s_lshl_b32 s14, s4, 7
	v_lshl_add_u64 v[66:67], v[122:123], 0, s[14:15]
	v_lshl_add_u64 v[68:69], v[124:125], 0, s[14:15]
	v_lshl_add_u64 v[70:71], v[126:127], 0, s[14:15]
	v_lshl_add_u64 v[72:73], v[128:129], 0, s[14:15]
	v_lshl_add_u64 v[74:75], v[130:131], 0, s[14:15]
	v_lshl_add_u64 v[82:83], v[132:133], 0, s[14:15]
	s_waitcnt lgkmcnt(0)
	s_barrier
	ds_read_b128 v[166:169], v0 offset:36864
	ds_read_b128 v[170:173], v139 offset:55296
	ds_read_b128 v[174:177], v139 offset:59904
	ds_read_b128 v[178:181], v0 offset:41472
	v_lshl_add_u64 v[154:155], v[134:135], 0, s[14:15]
	v_lshl_add_u64 v[156:157], v[136:137], 0, s[14:15]
	s_setprio 1
	ds_read_b128 v[182:185], v0 offset:36896
	ds_read_b128 v[186:189], v139 offset:55328
	ds_read_b128 v[190:193], v139 offset:59936
	ds_read_b128 v[194:197], v0 offset:41504
	s_waitcnt lgkmcnt(4)
	v_mfma_f32_32x32x16_bf16 v[50:65], v[166:169], v[170:173], v[50:65]
	global_load_dwordx4 v[78:81], v[66:67], off offset:384
	v_mfma_f32_32x32x16_bf16 v[34:49], v[166:169], v[174:177], v[34:49]
	global_load_dwordx4 v[86:89], v[68:69], off offset:384
	v_mfma_f32_32x32x16_bf16 v[18:33], v[178:181], v[170:173], v[18:33]
	global_load_dwordx4 v[90:93], v[70:71], off offset:384
	v_mfma_f32_32x32x16_bf16 v[2:17], v[178:181], v[174:177], v[2:17]
	global_load_dwordx4 v[94:97], v[72:73], off offset:384
	ds_read_b128 v[166:169], v0 offset:36928
	ds_read_b128 v[170:173], v139 offset:55360
	ds_read_b128 v[174:177], v139 offset:59968
	ds_read_b128 v[178:181], v0 offset:41536
	s_waitcnt lgkmcnt(4)
	v_mfma_f32_32x32x16_bf16 v[50:65], v[182:185], v[186:189], v[50:65]
	global_load_dwordx4 v[74:77], v[74:75], off offset:384
	s_waitcnt vmcnt(5)
	ds_write_b128 v138, v[98:101]
	v_mfma_f32_32x32x16_bf16 v[34:49], v[182:185], v[190:193], v[34:49]
	global_load_dwordx4 v[82:85], v[82:83], off offset:384
	ds_write_b128 v140, v[102:105]
	v_mfma_f32_32x32x16_bf16 v[18:33], v[194:197], v[186:189], v[18:33]
	global_load_dwordx4 v[66:69], v[154:155], off offset:384
	ds_write_b128 v142, v[106:109]
	v_mfma_f32_32x32x16_bf16 v[2:17], v[194:197], v[190:193], v[2:17]
	global_load_dwordx4 v[70:73], v[156:157], off offset:384
	ds_write_b128 v144, v[110:113]
	ds_read_b128 v[182:185], v0 offset:36960
	ds_read_b128 v[186:189], v139 offset:55392
	ds_read_b128 v[190:193], v139 offset:60000
	ds_read_b128 v[194:197], v0 offset:41568
	s_waitcnt lgkmcnt(8)
	v_mfma_f32_32x32x16_bf16 v[50:65], v[166:169], v[170:173], v[50:65]
	ds_write_b128 v138, v[114:117] offset:18432
	v_mfma_f32_32x32x16_bf16 v[34:49], v[166:169], v[174:177], v[34:49]
	ds_write_b128 v140, v[118:121] offset:18432
	v_mfma_f32_32x32x16_bf16 v[18:33], v[178:181], v[170:173], v[18:33]
	ds_write_b128 v142, v[150:153] offset:18432
	v_mfma_f32_32x32x16_bf16 v[2:17], v[178:181], v[174:177], v[2:17]
	ds_write_b128 v144, v[146:149] offset:18432
	s_waitcnt lgkmcnt(4)
	v_mfma_f32_32x32x16_bf16 v[50:65], v[182:185], v[186:189], v[50:65]
	v_mfma_f32_32x32x16_bf16 v[34:49], v[182:185], v[190:193], v[34:49]
	v_mfma_f32_32x32x16_bf16 v[18:33], v[194:197], v[186:189], v[18:33]
	v_mfma_f32_32x32x16_bf16 v[2:17], v[194:197], v[190:193], v[2:17]
	s_setprio 0
	s_cmp_lt_u32 s3, 14
	s_waitcnt lgkmcnt(0)
	s_cmp_lt_i32 s3, 12
	s_cbranch_scc0 .Lrot_exit_12
	s_branch .Lrot_body_12
.Lrot_exit_12:
	s_barrier

; #define TIDX (tid_launder())
; #define G_STORE(ST, S, unused) do { char* d_ = smem + (ST) * STAGE; \
;     *(uint4*)(d_ + alo[0]) = S##a0; *(uint4*)(d_ + alo[1]) = S##a1; *(uint4*)(d_ + alo[2]) = S##a2; *(uint4*)(d_ + alo[3]) = S##a3; \
;     *(uint4*)(d_ + blo[0]) = S##b0; *(uint4*)(d_ + blo[1]) = S##b1; \
;     if (NBCH == 4) { *(uint4*)(d_ + blo[NBCH - 2]) = S##b2; *(uint4*)(d_ + blo[NBCH - 1]) = S##b3; } } while (0)
; template <int NJ, class RowA>
; DI void gemm_main(f32x16 (&acc)[2][NJ], const bf16_t* __restrict__ A, RowA rowA, size_t kstrideA, int m0, int Mmax,
;                   const bf16_t* __restrict__ Bt, size_t ldb, int n0, int nk, char* smem) {
;     ...
;   const int tid = TIDX, lane = tid & 63, wid = tid >> 6, wm = wid >> 1, wn = wid & 1;
;   const int r = lane & 31, hh = lane >> 5;
;   const bf16_t* ap[4]; const bf16_t* bp[NBCH]; int alo[4], blo[NBCH];
; #pragma unroll
;   for (int i = 0; i < 4; ++i) {
;     const int c = tid + 256 * i, row = c >> 3, kc = c & 7;
;     int m = m0 + row; m = m < Mmax ? m : Mmax - 1;
;     ap[i] = A + rowA(m) + kc * 8; alo[i] = row * 144 + kc * 16;
;   }
; #pragma unroll
;   for (int i = 0; i < NBCH; ++i) {
;     const int c = tid + 256 * i, row = c >> 3, kc = c & 7;
;     bp[i] = Bt + (size_t)(n0 + row) * ldb + kc * 8; blo[i] = 128 * 144 + row * 144 + kc * 16;
;   }
; #pragma unroll
;   for (int i = 0; i < 2; ++i)
; #pragma unroll
;     for (int j = 0; j < NJ; ++j)
; #pragma unroll
;       for (int e = 0; e < 16; ++e) acc[i][j][e] = 0.f;
;   uint4 x0a0, x0a1, x0a2, x0a3, x0b0, x0b1, x0b2, x0b3, x1a0, x1a1, x1a2, x1a3, x1b0, x1b1, x1b2, x1b3;
;   x0b2 = x0b3 = x1b2 = x1b3 = make_uint4(0, 0, 0, 0);
;     ...
;   __syncthreads();
;   G_LOAD(x0, 0, 0);
;   G_LOAD(x1, 0, 1);
;   G_STORE(0, x0, 0);
;   __syncthreads();
.LBB0_18:
	v_readlane_b32 s16, v252, 9
	v_mov_b32_e32 v21, v230
	s_lshl_b32 s4, s3, 21
	v_readlane_b32 s24, v252, 17
	v_readlane_b32 s17, v252, 10
	v_ashrrev_i32_e32 v30, 3, v21
	v_readlane_b32 s18, v252, 11
	v_readlane_b32 s19, v252, 12
	v_readlane_b32 s20, v252, 13
	v_readlane_b32 s21, v252, 14
	v_readlane_b32 s22, v252, 15
	v_readlane_b32 s23, v252, 16
	v_readlane_b32 s25, v252, 18
	v_readlane_b32 s26, v252, 19
	v_readlane_b32 s27, v252, 20
	v_readlane_b32 s28, v252, 21
	v_readlane_b32 s29, v252, 22
	v_readlane_b32 s30, v252, 23
	v_readlane_b32 s31, v252, 24
	s_add_u32 s4, s24, s4
	v_add_u32_e32 v4, s1, v30
	s_addc_u32 s5, s25, 0
	v_lshlrev_b32_e32 v0, 4, v21
	v_readlane_b32 s16, v252, 57
	v_min_i32_e32 v4, 0x7fff, v4
	v_and_b32_e32 v0, 0x70, v0
	v_readlane_b32 s22, v252, 63
	v_readlane_b32 s23, v253, 0
	v_ashrrev_i32_e32 v5, 31, v4
	v_lshlrev_b64 v[4:5], 11, v[4:5]
	v_lshl_add_u64 v[2:3], s[22:23], 0, v[0:1]
	v_lshl_add_u64 v[58:59], v[2:3], 0, v[4:5]
	v_add_u32_e32 v4, 0x100, v21
	v_ashrrev_i32_e32 v31, 3, v4
	v_add_u32_e32 v4, s1, v31
	v_min_i32_e32 v4, 0x7fff, v4
	v_ashrrev_i32_e32 v5, 31, v4
	v_lshlrev_b64 v[4:5], 11, v[4:5]
	v_lshl_add_u64 v[60:61], v[2:3], 0, v[4:5]
	v_add_u32_e32 v4, 0x200, v21
	v_ashrrev_i32_e32 v32, 3, v4
	v_add_u32_e32 v4, s1, v32
	v_min_i32_e32 v4, 0x7fff, v4
	v_ashrrev_i32_e32 v5, 31, v4
	v_lshlrev_b64 v[4:5], 11, v[4:5]
	v_lshl_add_u64 v[62:63], v[2:3], 0, v[4:5]
	v_add_u32_e32 v4, 0x300, v21
	v_ashrrev_i32_e32 v33, 3, v4
	v_add_u32_e32 v4, s1, v33
	v_min_i32_e32 v4, 0x7fff, v4
	v_ashrrev_i32_e32 v5, 31, v4
	v_lshlrev_b64 v[4:5], 11, v[4:5]
	v_lshl_add_u64 v[64:65], v[2:3], 0, v[4:5]
	v_add_u32_e32 v4, s2, v30
	v_lshl_add_u64 v[2:3], s[4:5], 0, v[0:1]
	s_mov_b64 s[4:5], 0x840000
	v_ashrrev_i32_e32 v5, 31, v4
	v_lshl_add_u64 v[2:3], v[2:3], 0, s[4:5]
	v_lshlrev_b64 v[4:5], 11, v[4:5]
	s_waitcnt vmcnt(5)
	v_lshl_add_u64 v[66:67], v[2:3], 0, v[4:5]
	v_add_u32_e32 v4, s2, v31
	v_ashrrev_i32_e32 v5, 31, v4
	v_lshlrev_b64 v[4:5], 11, v[4:5]
	v_lshl_add_u64 v[68:69], v[2:3], 0, v[4:5]
	s_barrier
	global_load_dwordx4 v[2:5], v[58:59], off
	global_load_dwordx4 v[6:9], v[60:61], off
	global_load_dwordx4 v[10:13], v[62:63], off
	global_load_dwordx4 v[14:17], v[64:65], off
	global_load_dwordx4 v[22:25], v[66:67], off
	global_load_dwordx4 v[26:29], v[68:69], off
	global_load_dwordx4 v[34:37], v[58:59], off offset:128
	global_load_dwordx4 v[38:41], v[60:61], off offset:128
	global_load_dwordx4 v[42:45], v[62:63], off offset:128
	global_load_dwordx4 v[46:49], v[66:67], off offset:128
	global_load_dwordx4 v[50:53], v[68:69], off offset:128
	global_load_dwordx4 v[54:57], v[64:65], off offset:128
	s_waitcnt vmcnt(12)
	v_and_b32_e32 v70, 31, v21
	v_lshrrev_b32_e32 v21, 1, v21
	v_and_or_b32 v78, v21, s47, v70
	v_and_b32_e32 v79, 16, v21
	v_and_or_b32 v21, v21, 32, v70
	v_mad_u64_u32 v[70:71], s[6:7], v30, s76, v[0:1]
	v_mad_u64_u32 v[72:73], s[6:7], v31, s76, v[0:1]
	v_mad_u64_u32 v[74:75], s[6:7], v32, s76, v[0:1]
	v_mad_u64_u32 v[76:77], s[6:7], v33, s76, v[0:1]
	v_mul_u32_u24_e32 v21, 0x90, v21
	v_mul_lo_u32 v0, v78, s76
	s_mov_b32 s4, -2
	v_mov_b32_e32 v18, 0
	v_mov_b32_e32 v19, v142
	v_mov_b32_e32 v20, v142
	v_add_u32_e32 v0, v79, v0
	v_add_u32_e32 v71, v21, v79
	v_mov_b32_e32 v21, v142
	v_mov_b32_e32 v30, v142
	v_mov_b32_e32 v31, v142
	v_mov_b32_e32 v32, v142
	v_mov_b32_e32 v33, v142
	v_readlane_b32 s17, v252, 58
	v_readlane_b32 s18, v252, 59
	v_readlane_b32 s19, v252, 60
	v_readlane_b32 s20, v252, 61
	v_readlane_b32 s21, v252, 62
	v_readlane_b32 s24, v253, 1
	v_readlane_b32 s25, v253, 2
	v_readlane_b32 s26, v253, 3
	v_readlane_b32 s27, v253, 4
	s_waitcnt vmcnt(11)
	ds_write_b128 v70, v[2:5]
	s_waitcnt vmcnt(10)
	ds_write_b128 v72, v[6:9]
	s_waitcnt vmcnt(9)
	ds_write_b128 v74, v[10:13]
	s_waitcnt vmcnt(8)
	ds_write_b128 v76, v[14:17]
	s_waitcnt vmcnt(7)
	ds_write_b128 v70, v[22:25] offset:18432
	s_waitcnt vmcnt(6)
	ds_write_b128 v72, v[26:29] offset:18432
	v_mov_b32_e32 v22, v142
	v_mov_b32_e32 v23, v142
	v_mov_b32_e32 v24, v142
	v_mov_b32_e32 v25, v142
	v_mov_b32_e32 v26, v142
	v_mov_b32_e32 v27, v142
	v_mov_b32_e32 v28, v142
	v_mov_b32_e32 v29, v142
	v_mov_b32_e32 v2, 0
	v_mov_b32_e32 v3, v142
	v_mov_b32_e32 v4, v142
	v_mov_b32_e32 v5, v142
	v_mov_b32_e32 v6, v142
	v_mov_b32_e32 v7, v142
	v_mov_b32_e32 v8, v142
	v_mov_b32_e32 v9, v142
	v_mov_b32_e32 v10, v142
	v_mov_b32_e32 v11, v142
	v_mov_b32_e32 v12, v142
	v_mov_b32_e32 v13, v142
	v_mov_b32_e32 v14, v142
	v_mov_b32_e32 v15, v142
	v_mov_b32_e32 v16, v142
	v_mov_b32_e32 v17, v142
	v_readlane_b32 s28, v253, 5
	v_readlane_b32 s29, v253, 6
	v_readlane_b32 s30, v253, 7
	v_readlane_b32 s31, v253, 8
	s_waitcnt lgkmcnt(0)
; #define G_STORE(ST, S, unused) do { char* d_ = smem + (ST) * STAGE; \
;     *(uint4*)(d_ + alo[0]) = S##a0; *(uint4*)(d_ + alo[1]) = S##a1; *(uint4*)(d_ + alo[2]) = S##a2; *(uint4*)(d_ + alo[3]) = S##a3; \
;     *(uint4*)(d_ + blo[0]) = S##b0; *(uint4*)(d_ + blo[1]) = S##b1; \
;     if (NBCH == 4) { *(uint4*)(d_ + blo[NBCH - 2]) = S##b2; *(uint4*)(d_ + blo[NBCH - 1]) = S##b3; } } while (0)
; template <int NJ, class RowA>
; DI void gemm_main(f32x16 (&acc)[2][NJ], const bf16_t* __restrict__ A, RowA rowA, size_t kstrideA, int m0, int Mmax,
;                   const bf16_t* __restrict__ Bt, size_t ldb, int n0, int nk, char* smem) {
;     ...
; #pragma unroll 1
;   for (int kt = 0; kt < nk; kt += 2) {
;     G_LOAD(x0, 0, (kt + 2 < nk ? kt + 2 : nk - 1));
;     G_COMPUTE(0);
;     G_STORE(1, x1, 0);
;     __syncthreads();
;     G_LOAD(x1, 0, (kt + 3 < nk ? kt + 3 : nk - 1));
;     G_COMPUTE(1);
;     G_STORE(0, x0, 0);
;     __syncthreads();
;   }
.LBB0_19:
	s_cmp_lt_i32 s4, 12
	s_cbranch_scc0 .Lrot_exit_19
.Lrot_body_19:
	s_barrier
	ds_read_b128 v[176:179], v0
	ds_read_b128 v[180:183], v71 offset:18432
	ds_read_b128 v[184:187], v0 offset:4608
	s_add_i32 s5, s4, 4
	s_min_u32 s5, s5, 15
	s_lshl_b32 s14, s5, 7
	v_lshl_add_u64 v[78:79], v[58:59], 0, s[14:15]
	v_lshl_add_u64 v[82:83], v[60:61], 0, s[14:15]
	v_lshl_add_u64 v[86:87], v[62:63], 0, s[14:15]
	v_lshl_add_u64 v[122:123], v[64:65], 0, s[14:15]
	v_lshl_add_u64 v[126:127], v[66:67], 0, s[14:15]
	v_lshl_add_u64 v[130:131], v[68:69], 0, s[14:15]
	s_add_i32 s4, s4, 2
	s_setprio 1
	ds_read_b128 v[188:191], v0 offset:32
	ds_read_b128 v[192:195], v71 offset:18464
	ds_read_b128 v[196:199], v0 offset:4640
	s_waitcnt lgkmcnt(3)
	v_mfma_f32_32x32x16_bf16 v[18:33], v[176:179], v[180:183], v[18:33]
	global_load_dwordx4 v[78:81], v[78:79], off
	s_nop 0
	global_load_dwordx4 v[82:85], v[82:83], off
	v_mfma_f32_32x32x16_bf16 v[2:17], v[184:187], v[180:183], v[2:17]
	global_load_dwordx4 v[86:89], v[86:87], off
	ds_read_b128 v[176:179], v0 offset:64
	ds_read_b128 v[180:183], v71 offset:18496
	ds_read_b128 v[184:187], v0 offset:4672
	s_waitcnt lgkmcnt(3)
	v_mfma_f32_32x32x16_bf16 v[18:33], v[188:191], v[192:195], v[18:33]
	global_load_dwordx4 v[122:125], v[122:123], off
	s_nop 0
	global_load_dwordx4 v[126:129], v[126:127], off
	s_waitcnt vmcnt(5)
	ds_write_b128 v70, v[34:37] offset:27648
	ds_write_b128 v72, v[38:41] offset:27648
	v_mfma_f32_32x32x16_bf16 v[2:17], v[196:199], v[192:195], v[2:17]
	global_load_dwordx4 v[130:133], v[130:131], off
	ds_write_b128 v74, v[42:45] offset:27648
	ds_read_b128 v[188:191], v0 offset:96
	ds_read_b128 v[192:195], v71 offset:18528
	ds_read_b128 v[196:199], v0 offset:4704
	s_waitcnt lgkmcnt(6)
	v_mfma_f32_32x32x16_bf16 v[18:33], v[176:179], v[180:183], v[18:33]
	ds_write_b128 v76, v[54:57] offset:27648
	ds_write_b128 v70, v[46:49] offset:46080
	v_mfma_f32_32x32x16_bf16 v[2:17], v[184:187], v[180:183], v[2:17]
	ds_write_b128 v72, v[50:53] offset:46080
	s_waitcnt lgkmcnt(3)
	v_mfma_f32_32x32x16_bf16 v[18:33], v[188:191], v[192:195], v[18:33]
	v_mfma_f32_32x32x16_bf16 v[2:17], v[196:199], v[192:195], v[2:17]
	s_setprio 0
	s_min_u32 s5, s4, 12
	s_lshl_b32 s14, s5, 7
	v_lshl_add_u64 v[34:35], v[58:59], 0, s[14:15]
	v_lshl_add_u64 v[38:39], v[60:61], 0, s[14:15]
	v_lshl_add_u64 v[42:43], v[62:63], 0, s[14:15]
	v_lshl_add_u64 v[46:47], v[64:65], 0, s[14:15]
	v_lshl_add_u64 v[48:49], v[66:67], 0, s[14:15]
	v_lshl_add_u64 v[50:51], v[68:69], 0, s[14:15]
	s_waitcnt lgkmcnt(0)
	s_barrier
	ds_read_b128 v[176:179], v0 offset:27648
	ds_read_b128 v[180:183], v71 offset:46080
	ds_read_b128 v[184:187], v0 offset:32256
	s_setprio 1
	ds_read_b128 v[188:191], v0 offset:27680
	ds_read_b128 v[192:195], v71 offset:46112
	ds_read_b128 v[196:199], v0 offset:32288
	s_waitcnt lgkmcnt(3)
	v_mfma_f32_32x32x16_bf16 v[18:33], v[176:179], v[180:183], v[18:33]
	global_load_dwordx4 v[34:37], v[34:35], off offset:384
	s_nop 0
	global_load_dwordx4 v[38:41], v[38:39], off offset:384
	v_mfma_f32_32x32x16_bf16 v[2:17], v[184:187], v[180:183], v[2:17]
	global_load_dwordx4 v[42:45], v[42:43], off offset:384
	ds_read_b128 v[176:179], v0 offset:27712
	ds_read_b128 v[180:183], v71 offset:46144
	ds_read_b128 v[184:187], v0 offset:32320
	s_waitcnt lgkmcnt(3)
	v_mfma_f32_32x32x16_bf16 v[18:33], v[188:191], v[192:195], v[18:33]
	global_load_dwordx4 v[54:57], v[46:47], off offset:384
	s_nop 0
	global_load_dwordx4 v[46:49], v[48:49], off offset:384
	s_waitcnt vmcnt(5)
	ds_write_b128 v70, v[78:81]
	ds_write_b128 v72, v[82:85]
	v_mfma_f32_32x32x16_bf16 v[2:17], v[196:199], v[192:195], v[2:17]
	global_load_dwordx4 v[50:53], v[50:51], off offset:384
	ds_write_b128 v74, v[86:89]
	ds_read_b128 v[188:191], v0 offset:27744
	ds_read_b128 v[192:195], v71 offset:46176
	ds_read_b128 v[196:199], v0 offset:32352
	s_waitcnt lgkmcnt(6)
	v_mfma_f32_32x32x16_bf16 v[18:33], v[176:179], v[180:183], v[18:33]
	ds_write_b128 v76, v[122:125]
	ds_write_b128 v70, v[126:129] offset:18432
	v_mfma_f32_32x32x16_bf16 v[2:17], v[184:187], v[180:183], v[2:17]
	ds_write_b128 v72, v[130:133] offset:18432
	s_waitcnt lgkmcnt(3)
	v_mfma_f32_32x32x16_bf16 v[18:33], v[188:191], v[192:195], v[18:33]
	v_mfma_f32_32x32x16_bf16 v[2:17], v[196:199], v[192:195], v[2:17]
	s_setprio 0
	s_cmp_lt_u32 s4, 14
	s_waitcnt lgkmcnt(0)
	s_cmp_lt_i32 s4, 12
	s_cbranch_scc0 .Lrot_exit_19
	s_branch .Lrot_body_19

; #define G_STORE(ST, S, unused) do { char* d_ = smem + (ST) * STAGE; \
;     *(uint4*)(d_ + alo[0]) = S##a0; *(uint4*)(d_ + alo[1]) = S##a1; *(uint4*)(d_ + alo[2]) = S##a2; *(uint4*)(d_ + alo[3]) = S##a3; \
;     *(uint4*)(d_ + blo[0]) = S##b0; *(uint4*)(d_ + blo[1]) = S##b1; \
;     if (NBCH == 4) { *(uint4*)(d_ + blo[NBCH - 2]) = S##b2; *(uint4*)(d_ + blo[NBCH - 1]) = S##b3; } } while (0)
; template <int NJ, class RowA>
; DI void gemm_main(f32x16 (&acc)[2][NJ], const bf16_t* __restrict__ A, RowA rowA, size_t kstrideA, int m0, int Mmax,
;                   const bf16_t* __restrict__ Bt, size_t ldb, int n0, int nk, char* smem) {
;     ...
;   for (int kt = 0; kt < nk; kt += 2) {
;     G_LOAD(x0, 0, (kt + 2 < nk ? kt + 2 : nk - 1));
;     G_COMPUTE(0);
;     G_STORE(1, x1, 0);
;     __syncthreads();
;     G_LOAD(x1, 0, (kt + 3 < nk ? kt + 3 : nk - 1));
;     G_COMPUTE(1);
;     G_STORE(0, x0, 0);
;     __syncthreads();
;   }
; DI void merge_tile(const Params& p, int mt, int nt, char* smem) {
;     ...
;   for (int x = 0; x < 3; ++x) {
;     const int koff = x == 0 ? 0 : (x == 1 ? 256 : 768);
;     const int nkp = x == 1 ? 8 : 4;
;     f32x16 ag[2][1], ap[2][1];
;     gemm_main<1>(ag, p.h, RowLin{1024}, 64, m0, T_TOK, p.wt_in + (size_t)(4224 + x * 1024) * 1024, 1024, n0, 16, smem);
;     gemm_main<1>(ap, p.projZ + koff, RowLin{LDA_Z}, 64, m0, T_TOK, p.wt_br + koff, 1024, n0, nkp, smem);
.Lpeel_tail_19:
	ds_read_b128 v[176:179], v0
	ds_read_b128 v[180:183], v71 offset:18432
	ds_read_b128 v[184:187], v0 offset:4608
	s_add_i32 s5, s4, 4
	s_min_u32 s5, s5, 15
	s_lshl_b32 s14, s5, 7
	v_lshl_add_u64 v[78:79], v[58:59], 0, s[14:15]
	v_lshl_add_u64 v[82:83], v[60:61], 0, s[14:15]
	v_lshl_add_u64 v[86:87], v[62:63], 0, s[14:15]
	v_lshl_add_u64 v[122:123], v[64:65], 0, s[14:15]
	v_lshl_add_u64 v[126:127], v[66:67], 0, s[14:15]
	v_lshl_add_u64 v[130:131], v[68:69], 0, s[14:15]
	s_add_i32 s4, s4, 2
	s_setprio 1
	ds_read_b128 v[188:191], v0 offset:32
	ds_read_b128 v[192:195], v71 offset:18464
	ds_read_b128 v[196:199], v0 offset:4640
	s_waitcnt lgkmcnt(3)
	v_mfma_f32_32x32x16_bf16 v[18:33], v[176:179], v[180:183], v[18:33]
	v_mfma_f32_32x32x16_bf16 v[2:17], v[184:187], v[180:183], v[2:17]
	ds_read_b128 v[176:179], v0 offset:64
	ds_read_b128 v[180:183], v71 offset:18496
	ds_read_b128 v[184:187], v0 offset:4672
	s_waitcnt lgkmcnt(3)
	v_mfma_f32_32x32x16_bf16 v[18:33], v[188:191], v[192:195], v[18:33]
	v_mfma_f32_32x32x16_bf16 v[2:17], v[196:199], v[192:195], v[2:17]
	ds_read_b128 v[188:191], v0 offset:96
	ds_read_b128 v[192:195], v71 offset:18528
	ds_read_b128 v[196:199], v0 offset:4704
	s_waitcnt lgkmcnt(3)
	v_mfma_f32_32x32x16_bf16 v[18:33], v[176:179], v[180:183], v[18:33]
	s_waitcnt vmcnt(0)
	ds_write_b128 v70, v[34:37] offset:27648
	ds_write_b128 v72, v[38:41] offset:27648
	v_mfma_f32_32x32x16_bf16 v[2:17], v[184:187], v[180:183], v[2:17]
	ds_write_b128 v74, v[42:45] offset:27648
	s_waitcnt lgkmcnt(3)
	v_mfma_f32_32x32x16_bf16 v[18:33], v[188:191], v[192:195], v[18:33]
	ds_write_b128 v76, v[54:57] offset:27648
	ds_write_b128 v70, v[46:49] offset:46080
	v_mfma_f32_32x32x16_bf16 v[2:17], v[196:199], v[192:195], v[2:17]
	ds_write_b128 v72, v[50:53] offset:46080
	s_setprio 0
	s_min_u32 s5, s4, 12
	s_lshl_b32 s14, s5, 7
	v_lshl_add_u64 v[34:35], v[58:59], 0, s[14:15]
	v_lshl_add_u64 v[38:39], v[60:61], 0, s[14:15]
	v_lshl_add_u64 v[42:43], v[62:63], 0, s[14:15]
	v_lshl_add_u64 v[46:47], v[64:65], 0, s[14:15]
	v_lshl_add_u64 v[48:49], v[66:67], 0, s[14:15]
	v_lshl_add_u64 v[50:51], v[68:69], 0, s[14:15]
	s_waitcnt lgkmcnt(0)
	s_barrier
	ds_read_b128 v[176:179], v0 offset:27648
	ds_read_b128 v[180:183], v71 offset:46080
	ds_read_b128 v[184:187], v0 offset:32256
	s_setprio 1
	ds_read_b128 v[188:191], v0 offset:27680
	ds_read_b128 v[192:195], v71 offset:46112
	ds_read_b128 v[196:199], v0 offset:32288
	s_waitcnt lgkmcnt(3)
	v_mfma_f32_32x32x16_bf16 v[18:33], v[176:179], v[180:183], v[18:33]
	v_mfma_f32_32x32x16_bf16 v[2:17], v[184:187], v[180:183], v[2:17]
	ds_read_b128 v[176:179], v0 offset:27712
	ds_read_b128 v[180:183], v71 offset:46144
	ds_read_b128 v[184:187], v0 offset:32320
	s_waitcnt lgkmcnt(3)
	v_mfma_f32_32x32x16_bf16 v[18:33], v[188:191], v[192:195], v[18:33]
	v_mfma_f32_32x32x16_bf16 v[2:17], v[196:199], v[192:195], v[2:17]
	ds_read_b128 v[188:191], v0 offset:27744
	ds_read_b128 v[192:195], v71 offset:46176
	ds_read_b128 v[196:199], v0 offset:32352
	s_waitcnt lgkmcnt(3)
	v_mfma_f32_32x32x16_bf16 v[18:33], v[176:179], v[180:183], v[18:33]
	v_mfma_f32_32x32x16_bf16 v[2:17], v[184:187], v[180:183], v[2:17]
	s_waitcnt lgkmcnt(0)
	v_mfma_f32_32x32x16_bf16 v[18:33], v[188:191], v[192:195], v[18:33]
	v_mfma_f32_32x32x16_bf16 v[2:17], v[196:199], v[192:195], v[2:17]
	s_setprio 0
	s_cmp_lt_u32 s4, 14
	s_waitcnt lgkmcnt(0)
	s_barrier
	s_cmp_eq_u32 s3, 1
	s_cselect_b32 s5, s42, 0x300
	s_cselect_b32 s4, 8, 4
	s_cmp_lg_u32 s3, 0
	v_mov_b32_e32 v58, v230
	s_cselect_b32 s5, s5, 0
	v_readlane_b32 s16, v252, 57
	s_lshl_b32 s5, s5, 1
	v_ashrrev_i32_e32 v59, 3, v58
	v_readlane_b32 s28, v253, 5
	s_waitcnt vmcnt(5)
	v_add_u32_e32 v36, s1, v59
	v_readlane_b32 s29, v253, 6
	s_add_u32 s6, s28, s5
	v_lshlrev_b32_e32 v0, 4, v58
	v_min_i32_e32 v36, 0x7fff, v36
	s_addc_u32 s7, s29, 0
	v_and_b32_e32 v0, 0x70, v0
	v_ashrrev_i32_e32 v37, 31, v36
	v_lshl_add_u64 v[34:35], s[6:7], 0, v[0:1]
	v_lshlrev_b64 v[36:37], 11, v[36:37]
	v_lshl_add_u64 v[122:123], v[34:35], 0, v[36:37]
	v_add_u32_e32 v36, 0x100, v58
	v_ashrrev_i32_e32 v60, 3, v36
	v_add_u32_e32 v36, s1, v60
	v_min_i32_e32 v36, 0x7fff, v36
	v_ashrrev_i32_e32 v37, 31, v36
	v_lshlrev_b64 v[36:37], 11, v[36:37]
	v_lshl_add_u64 v[124:125], v[34:35], 0, v[36:37]
	v_add_u32_e32 v36, 0x200, v58
	v_ashrrev_i32_e32 v61, 3, v36
	v_add_u32_e32 v36, s1, v61
	v_min_i32_e32 v36, 0x7fff, v36
	v_ashrrev_i32_e32 v37, 31, v36
	v_lshlrev_b64 v[36:37], 11, v[36:37]
	v_lshl_add_u64 v[126:127], v[34:35], 0, v[36:37]
	v_add_u32_e32 v36, 0x300, v58
	v_ashrrev_i32_e32 v62, 3, v36
	v_add_u32_e32 v36, s1, v62
	v_min_i32_e32 v36, 0x7fff, v36
	v_ashrrev_i32_e32 v37, 31, v36
	v_lshlrev_b64 v[36:37], 11, v[36:37]
	v_readlane_b32 s17, v252, 58
	s_add_u32 s8, s16, s5
	v_lshl_add_u64 v[128:129], v[34:35], 0, v[36:37]
	v_add_u32_e32 v36, s2, v59
	s_addc_u32 s9, s17, 0
	v_ashrrev_i32_e32 v37, 31, v36
	v_lshl_add_u64 v[34:35], s[8:9], 0, v[0:1]
	v_lshlrev_b64 v[36:37], 11, v[36:37]
	v_lshl_add_u64 v[130:131], v[34:35], 0, v[36:37]
	v_add_u32_e32 v36, s2, v60
	v_ashrrev_i32_e32 v37, 31, v36
	v_lshlrev_b64 v[36:37], 11, v[36:37]
	v_lshl_add_u64 v[132:133], v[34:35], 0, v[36:37]
	s_barrier
; #define TIDX (tid_launder())
; #define G_STORE(ST, S, unused) do { char* d_ = smem + (ST) * STAGE; \
;     *(uint4*)(d_ + alo[0]) = S##a0; *(uint4*)(d_ + alo[1]) = S##a1; *(uint4*)(d_ + alo[2]) = S##a2; *(uint4*)(d_ + alo[3]) = S##a3; \
;     *(uint4*)(d_ + blo[0]) = S##b0; *(uint4*)(d_ + blo[1]) = S##b1; \
;     if (NBCH == 4) { *(uint4*)(d_ + blo[NBCH - 2]) = S##b2; *(uint4*)(d_ + blo[NBCH - 1]) = S##b3; } } while (0)
; template <int NJ, class RowA>
; DI void gemm_main(f32x16 (&acc)[2][NJ], const bf16_t* __restrict__ A, RowA rowA, size_t kstrideA, int m0, int Mmax,
;                   const bf16_t* __restrict__ Bt, size_t ldb, int n0, int nk, char* smem) {
;     ...
;   const int tid = TIDX, lane = tid & 63, wid = tid >> 6, wm = wid >> 1, wn = wid & 1;
;   const int r = lane & 31, hh = lane >> 5;
;   const bf16_t* ap[4]; const bf16_t* bp[NBCH]; int alo[4], blo[NBCH];
; #pragma unroll
;   for (int i = 0; i < 4; ++i) {
;     const int c = tid + 256 * i, row = c >> 3, kc = c & 7;
;     int m = m0 + row; m = m < Mmax ? m : Mmax - 1;
;     ap[i] = A + rowA(m) + kc * 8; alo[i] = row * 144 + kc * 16;
;   }
; #pragma unroll
;   for (int i = 0; i < NBCH; ++i) {
;     const int c = tid + 256 * i, row = c >> 3, kc = c & 7;
;     bp[i] = Bt + (size_t)(n0 + row) * ldb + kc * 8; blo[i] = 128 * 144 + row * 144 + kc * 16;
;   }
; #pragma unroll
;   for (int i = 0; i < 2; ++i)
; #pragma unroll
;     for (int j = 0; j < NJ; ++j)
; #pragma unroll
;       for (int e = 0; e < 16; ++e) acc[i][j][e] = 0.f;
;   uint4 x0a0, x0a1, x0a2, x0a3, x0b0, x0b1, x0b2, x0b3, x1a0, x1a1, x1a2, x1a3, x1b0, x1b1, x1b2, x1b3;
;   x0b2 = x0b3 = x1b2 = x1b3 = make_uint4(0, 0, 0, 0);
;     ...
;   __syncthreads();
;   G_LOAD(x0, 0, 0);
;   G_LOAD(x1, 0, 1);
;   G_STORE(0, x0, 0);
;   __syncthreads();
; #pragma unroll 1
;   for (int kt = 0; kt < nk; kt += 2) {
	global_load_dwordx4 v[34:37], v[122:123], off
	global_load_dwordx4 v[38:41], v[124:125], off
	global_load_dwordx4 v[42:45], v[126:127], off
	global_load_dwordx4 v[46:49], v[128:129], off
	global_load_dwordx4 v[50:53], v[130:131], off
	global_load_dwordx4 v[54:57], v[132:133], off
	global_load_dwordx4 v[66:69], v[122:123], off offset:128
	global_load_dwordx4 v[70:73], v[124:125], off offset:128
	global_load_dwordx4 v[74:77], v[126:127], off offset:128
	global_load_dwordx4 v[78:81], v[128:129], off offset:128
	global_load_dwordx4 v[82:85], v[130:131], off offset:128
	global_load_dwordx4 v[86:89], v[132:133], off offset:128
	v_and_b32_e32 v63, 31, v58
	v_lshrrev_b32_e32 v58, 1, v58
	v_and_or_b32 v64, v58, s47, v63
	v_and_b32_e32 v65, 16, v58
	v_and_or_b32 v58, v58, 32, v63
	v_mad_u64_u32 v[134:135], s[6:7], v59, s76, v[0:1]
	v_mad_u64_u32 v[136:137], s[6:7], v60, s76, v[0:1]
	v_mad_u64_u32 v[138:139], s[6:7], v61, s76, v[0:1]
	v_mad_u64_u32 v[140:141], s[6:7], v62, s76, v[0:1]
	v_mul_u32_u24_e32 v58, 0x90, v58
	v_mul_lo_u32 v0, v64, s76
	s_mov_b32 s5, 3
	s_add_i32 s6, s4, -1
	v_add_u32_e32 v0, v65, v0
	v_add_u32_e32 v135, v58, v65
	v_readlane_b32 s18, v252, 59
	v_readlane_b32 s19, v252, 60
	v_readlane_b32 s20, v252, 61
	v_readlane_b32 s21, v252, 62
	v_readlane_b32 s22, v252, 63
	v_readlane_b32 s23, v253, 0
	v_readlane_b32 s24, v253, 1
	v_readlane_b32 s25, v253, 2
	v_readlane_b32 s26, v253, 3
	v_readlane_b32 s27, v253, 4
	v_readlane_b32 s30, v253, 7
	v_readlane_b32 s31, v253, 8
	s_waitcnt vmcnt(11)
	ds_write_b128 v134, v[34:37]
	s_waitcnt vmcnt(10)
	ds_write_b128 v136, v[38:41]
	s_waitcnt vmcnt(9)
	ds_write_b128 v138, v[42:45]
	s_waitcnt vmcnt(8)
	ds_write_b128 v140, v[46:49]
	s_waitcnt vmcnt(7)
	ds_write_b128 v134, v[50:53] offset:18432
	s_waitcnt vmcnt(6)
	ds_write_b128 v136, v[54:57] offset:18432
	v_mov_b32_e32 v34, 0
	v_mov_b32_e32 v35, v34
	v_mov_b32_e32 v36, v34
	v_mov_b32_e32 v37, v34
	v_mov_b32_e32 v38, v34
	v_mov_b32_e32 v39, v34
	v_mov_b32_e32 v40, v34
	v_mov_b32_e32 v41, v34
	v_mov_b32_e32 v42, v34
	v_mov_b32_e32 v43, v34
	v_mov_b32_e32 v44, v34
	v_mov_b32_e32 v45, v34
	v_mov_b32_e32 v46, v34
	v_mov_b32_e32 v47, v34
	v_mov_b32_e32 v48, v34
	v_mov_b32_e32 v49, v34
	v_mov_b32_e32 v50, v34
	v_mov_b32_e32 v51, v34
	v_mov_b32_e32 v52, v34
	v_mov_b32_e32 v53, v34
	v_mov_b32_e32 v54, v34
	v_mov_b32_e32 v55, v34
	v_mov_b32_e32 v56, v34
	v_mov_b32_e32 v57, v34
	v_mov_b32_e32 v58, v34
	v_mov_b32_e32 v59, v34
	v_mov_b32_e32 v60, v34
	v_mov_b32_e32 v61, v34
	v_mov_b32_e32 v62, v34
	v_mov_b32_e32 v63, v34
	v_mov_b32_e32 v64, v34
	v_mov_b32_e32 v65, v34
	s_waitcnt lgkmcnt(0)
.LBB0_21:
	s_add_i32 s7, s5, -1
	s_cmp_lt_u32 s7, s4
	s_cbranch_scc0 .Lrot_exit_21
; #define G_STORE(ST, S, unused) do { char* d_ = smem + (ST) * STAGE; \
;     *(uint4*)(d_ + alo[0]) = S##a0; *(uint4*)(d_ + alo[1]) = S##a1; *(uint4*)(d_ + alo[2]) = S##a2; *(uint4*)(d_ + alo[3]) = S##a3; \
;     *(uint4*)(d_ + blo[0]) = S##b0; *(uint4*)(d_ + blo[1]) = S##b1; \
;     if (NBCH == 4) { *(uint4*)(d_ + blo[NBCH - 2]) = S##b2; *(uint4*)(d_ + blo[NBCH - 1]) = S##b3; } } while (0)
; template <int NJ, class RowA>
; DI void gemm_main(f32x16 (&acc)[2][NJ], const bf16_t* __restrict__ A, RowA rowA, size_t kstrideA, int m0, int Mmax,
;                   const bf16_t* __restrict__ Bt, size_t ldb, int n0, int nk, char* smem) {
;     ...
; #pragma unroll 1
;   for (int kt = 0; kt < nk; kt += 2) {
;     G_LOAD(x0, 0, (kt + 2 < nk ? kt + 2 : nk - 1));
;     G_COMPUTE(0);
;     G_STORE(1, x1, 0);
;     __syncthreads();
;     G_LOAD(x1, 0, (kt + 3 < nk ? kt + 3 : nk - 1));
;     G_COMPUTE(1);
;     G_STORE(0, x0, 0);
;     __syncthreads();
;   }
.Lrot_body_21:
	s_barrier
	ds_read_b128 v[176:179], v0
	ds_read_b128 v[180:183], v135 offset:18432
	ds_read_b128 v[184:187], v0 offset:4608
	s_add_i32 s7, s5, -1
	s_min_u32 s14, s7, s6
	s_lshl_b64 s[8:9], s[14:15], 7
	v_lshl_add_u64 v[144:145], v[122:123], 0, s[8:9]
	v_lshl_add_u64 v[148:149], v[124:125], 0, s[8:9]
	v_lshl_add_u64 v[152:153], v[126:127], 0, s[8:9]
	v_lshl_add_u64 v[156:157], v[128:129], 0, s[8:9]
	v_lshl_add_u64 v[160:161], v[130:131], 0, s[8:9]
	v_lshl_add_u64 v[164:165], v[132:133], 0, s[8:9]
	s_setprio 1
	ds_read_b128 v[188:191], v0 offset:32
	ds_read_b128 v[192:195], v135 offset:18464
	ds_read_b128 v[196:199], v0 offset:4640
	s_waitcnt lgkmcnt(3)
	v_mfma_f32_32x32x16_bf16 v[50:65], v[176:179], v[180:183], v[50:65]
	global_load_dwordx4 v[144:147], v[144:145], off
	s_nop 0
	global_load_dwordx4 v[148:151], v[148:149], off
	v_mfma_f32_32x32x16_bf16 v[34:49], v[184:187], v[180:183], v[34:49]
	global_load_dwordx4 v[152:155], v[152:153], off
	ds_read_b128 v[176:179], v0 offset:64
	ds_read_b128 v[180:183], v135 offset:18496
	ds_read_b128 v[184:187], v0 offset:4672
	s_waitcnt lgkmcnt(3)
	v_mfma_f32_32x32x16_bf16 v[50:65], v[188:191], v[192:195], v[50:65]
	global_load_dwordx4 v[156:159], v[156:157], off
	s_nop 0
	global_load_dwordx4 v[160:163], v[160:161], off
	s_waitcnt vmcnt(5)
	ds_write_b128 v134, v[66:69] offset:27648
	ds_write_b128 v136, v[70:73] offset:27648
	v_mfma_f32_32x32x16_bf16 v[34:49], v[196:199], v[192:195], v[34:49]
	global_load_dwordx4 v[164:167], v[164:165], off
	ds_write_b128 v138, v[74:77] offset:27648
	ds_read_b128 v[188:191], v0 offset:96
	ds_read_b128 v[192:195], v135 offset:18528
	ds_read_b128 v[196:199], v0 offset:4704
	s_waitcnt lgkmcnt(6)
	v_mfma_f32_32x32x16_bf16 v[50:65], v[176:179], v[180:183], v[50:65]
	ds_write_b128 v140, v[78:81] offset:27648
	ds_write_b128 v134, v[82:85] offset:46080
	v_mfma_f32_32x32x16_bf16 v[34:49], v[184:187], v[180:183], v[34:49]
	ds_write_b128 v136, v[86:89] offset:46080
	s_waitcnt lgkmcnt(3)
	v_mfma_f32_32x32x16_bf16 v[50:65], v[188:191], v[192:195], v[50:65]
	v_mfma_f32_32x32x16_bf16 v[34:49], v[196:199], v[192:195], v[34:49]
	s_setprio 0
	s_min_u32 s14, s5, s6
	s_lshl_b64 s[8:9], s[14:15], 7
	v_lshl_add_u64 v[66:67], v[122:123], 0, s[8:9]
	v_lshl_add_u64 v[70:71], v[124:125], 0, s[8:9]
	v_lshl_add_u64 v[74:75], v[126:127], 0, s[8:9]
	v_lshl_add_u64 v[78:79], v[128:129], 0, s[8:9]
	v_lshl_add_u64 v[82:83], v[130:131], 0, s[8:9]
	v_lshl_add_u64 v[86:87], v[132:133], 0, s[8:9]
	s_waitcnt lgkmcnt(0)
	s_barrier
	ds_read_b128 v[176:179], v0 offset:27648
	ds_read_b128 v[180:183], v135 offset:46080
	ds_read_b128 v[184:187], v0 offset:32256
	s_setprio 1
	ds_read_b128 v[188:191], v0 offset:27680
	ds_read_b128 v[192:195], v135 offset:46112
	ds_read_b128 v[196:199], v0 offset:32288
	s_waitcnt lgkmcnt(3)
	v_mfma_f32_32x32x16_bf16 v[50:65], v[176:179], v[180:183], v[50:65]
	global_load_dwordx4 v[66:69], v[66:67], off
	s_nop 0
	global_load_dwordx4 v[70:73], v[70:71], off
	v_mfma_f32_32x32x16_bf16 v[34:49], v[184:187], v[180:183], v[34:49]
	global_load_dwordx4 v[74:77], v[74:75], off
	ds_read_b128 v[176:179], v0 offset:27712
	ds_read_b128 v[180:183], v135 offset:46144
	ds_read_b128 v[184:187], v0 offset:32320
	s_waitcnt lgkmcnt(3)
	v_mfma_f32_32x32x16_bf16 v[50:65], v[188:191], v[192:195], v[50:65]
	global_load_dwordx4 v[78:81], v[78:79], off
	s_nop 0
	global_load_dwordx4 v[82:85], v[82:83], off
	s_waitcnt vmcnt(5)
	ds_write_b128 v134, v[144:147]
	ds_write_b128 v136, v[148:151]
	v_mfma_f32_32x32x16_bf16 v[34:49], v[196:199], v[192:195], v[34:49]
	global_load_dwordx4 v[86:89], v[86:87], off
	ds_write_b128 v138, v[152:155]
	ds_read_b128 v[188:191], v0 offset:27744
	ds_read_b128 v[192:195], v135 offset:46176
	ds_read_b128 v[196:199], v0 offset:32352
	s_waitcnt lgkmcnt(6)
	v_mfma_f32_32x32x16_bf16 v[50:65], v[176:179], v[180:183], v[50:65]
	ds_write_b128 v140, v[156:159]
	ds_write_b128 v134, v[160:163] offset:18432
	v_mfma_f32_32x32x16_bf16 v[34:49], v[184:187], v[180:183], v[34:49]
	ds_write_b128 v136, v[164:167] offset:18432
	s_waitcnt lgkmcnt(3)
	v_mfma_f32_32x32x16_bf16 v[50:65], v[188:191], v[192:195], v[50:65]
	v_mfma_f32_32x32x16_bf16 v[34:49], v[196:199], v[192:195], v[34:49]
	s_setprio 0
	s_add_i32 s5, s5, 2
	s_cmp_lt_u32 s7, s4
	s_waitcnt lgkmcnt(0)
	s_add_i32 s7, s5, -1
	s_cmp_lt_u32 s7, s4
	s_cbranch_scc0 .Lrot_exit_21
	s_branch .Lrot_body_21

; #define TIDX (tid_launder())
; #define G_STORE(ST, S, unused) do { char* d_ = smem + (ST) * STAGE; \
;     *(uint4*)(d_ + alo[0]) = S##a0; *(uint4*)(d_ + alo[1]) = S##a1; *(uint4*)(d_ + alo[2]) = S##a2; *(uint4*)(d_ + alo[3]) = S##a3; \
;     *(uint4*)(d_ + blo[0]) = S##b0; *(uint4*)(d_ + blo[1]) = S##b1; \
;     if (NBCH == 4) { *(uint4*)(d_ + blo[NBCH - 2]) = S##b2; *(uint4*)(d_ + blo[NBCH - 1]) = S##b3; } } while (0)
; template <int NJ, class RowA>
; DI void gemm_main(f32x16 (&acc)[2][NJ], const bf16_t* __restrict__ A, RowA rowA, size_t kstrideA, int m0, int Mmax,
;                   const bf16_t* __restrict__ Bt, size_t ldb, int n0, int nk, char* smem) {
;     ...
;   const int tid = TIDX, lane = tid & 63, wid = tid >> 6, wm = wid >> 1, wn = wid & 1;
;   const int r = lane & 31, hh = lane >> 5;
;   const bf16_t* ap[4]; const bf16_t* bp[NBCH]; int alo[4], blo[NBCH];
; #pragma unroll
;   for (int i = 0; i < 4; ++i) {
;     const int c = tid + 256 * i, row = c >> 3, kc = c & 7;
;     int m = m0 + row; m = m < Mmax ? m : Mmax - 1;
;     ap[i] = A + rowA(m) + kc * 8; alo[i] = row * 144 + kc * 16;
;   }
; #pragma unroll
;   for (int i = 0; i < NBCH; ++i) {
;     const int c = tid + 256 * i, row = c >> 3, kc = c & 7;
;     bp[i] = Bt + (size_t)(n0 + row) * ldb + kc * 8; blo[i] = 128 * 144 + row * 144 + kc * 16;
;   }
; #pragma unroll
;   for (int i = 0; i < 2; ++i)
; #pragma unroll
;     for (int j = 0; j < NJ; ++j)
; #pragma unroll
;       for (int e = 0; e < 16; ++e) acc[i][j][e] = 0.f;
;   uint4 x0a0, x0a1, x0a2, x0a3, x0b0, x0b1, x0b2, x0b3, x1a0, x1a1, x1a2, x1a3, x1b0, x1b1, x1b2, x1b3;
;   x0b2 = x0b3 = x1b2 = x1b3 = make_uint4(0, 0, 0, 0);
;     ...
;   __syncthreads();
;   G_LOAD(x0, 0, 0);
;   G_LOAD(x1, 0, 1);
;   G_STORE(0, x0, 0);
;   __syncthreads();
; DI void phase_inproj(const Params& p, int l, bool partB, int skipb, char* smem) {
;     ...
;   for (int idx = vblk >> 3; idx < per; idx += nvb >> 3) {
;     const int t = (vblk & 7) * per + idx;
;     const int mt = t / ntn; int tn = t % ntn;
;     if (partB) tn += 12; else if (tn >= 12) tn += 13;
;     inproj_tile(p, l, mt, tn, smem);
.LBB0_1955:
	v_readlane_b32 s0, v251, 50
	s_add_i32 s0, s10, s0
	s_mul_hi_i32 s3, s0, 0x66666667
	s_lshr_b32 s4, s3, 31
	s_ashr_i32 s1, s3, 3
	s_add_i32 s1, s1, s4
	s_mul_i32 s2, s1, 20
	s_sub_i32 s0, s0, s2
	s_add_i32 s2, s0, 13
	s_cmp_gt_i32 s0, 11
	v_mov_b32_e32 v34, v230
	s_cselect_b32 s12, s2, s0
	s_lshl_b32 s11, s1, 7
	v_readlane_b32 s16, v252, 57
	v_ashrrev_i32_e32 v35, 3, v34
	v_add_u32_e32 v4, s11, v35
	v_lshlrev_b32_e32 v0, 4, v34
	v_min_i32_e32 v4, 0x7fff, v4
	v_and_b32_e32 v0, 0x70, v0
	v_readlane_b32 s22, v252, 63
	v_readlane_b32 s23, v253, 0
	v_ashrrev_i32_e32 v5, 31, v4
	v_lshlrev_b64 v[4:5], 11, v[4:5]
	v_lshl_add_u64 v[2:3], s[22:23], 0, v[0:1]
	v_lshl_add_u64 v[122:123], v[2:3], 0, v[4:5]
	v_add_u32_e32 v4, 0x100, v34
	v_ashrrev_i32_e32 v36, 3, v4
	v_add_u32_e32 v4, s11, v36
	v_min_i32_e32 v4, 0x7fff, v4
	v_ashrrev_i32_e32 v5, 31, v4
	v_lshlrev_b64 v[4:5], 11, v[4:5]
	v_lshl_add_u64 v[124:125], v[2:3], 0, v[4:5]
	v_add_u32_e32 v4, 0x200, v34
	v_ashrrev_i32_e32 v37, 3, v4
	v_add_u32_e32 v4, s11, v37
	v_min_i32_e32 v4, 0x7fff, v4
	v_ashrrev_i32_e32 v5, 31, v4
	v_lshlrev_b64 v[4:5], 11, v[4:5]
	v_lshl_add_u64 v[126:127], v[2:3], 0, v[4:5]
	v_add_u32_e32 v4, 0x300, v34
	v_ashrrev_i32_e32 v38, 3, v4
	v_add_u32_e32 v4, s11, v38
	v_min_i32_e32 v4, 0x7fff, v4
	v_ashrrev_i32_e32 v5, 31, v4
	s_lshl_b32 s2, s12, 7
	v_readlane_b32 s17, v252, 58
	v_readlane_b32 s18, v252, 59
	v_readlane_b32 s19, v252, 60
	v_readlane_b32 s20, v252, 61
	v_readlane_b32 s21, v252, 62
	v_readlane_b32 s24, v253, 1
	v_readlane_b32 s25, v253, 2
	v_readlane_b32 s26, v253, 3
	v_readlane_b32 s27, v253, 4
	v_readlane_b32 s28, v253, 5
	v_readlane_b32 s29, v253, 6
	v_readlane_b32 s30, v253, 7
	v_readlane_b32 s31, v253, 8
	v_lshlrev_b64 v[4:5], 11, v[4:5]
	v_lshl_add_u64 v[128:129], v[2:3], 0, v[4:5]
	v_readlane_b32 s16, v252, 9
	v_add_u32_e32 v4, s2, v35
	v_readlane_b32 s24, v252, 17
	v_readlane_b32 s25, v252, 18
	v_ashrrev_i32_e32 v5, 31, v4
	v_lshlrev_b64 v[4:5], 11, v[4:5]
	v_lshl_add_u64 v[2:3], s[24:25], 0, v[0:1]
	v_lshl_add_u64 v[130:131], v[2:3], 0, v[4:5]
	v_add_u32_e32 v4, s2, v36
	v_ashrrev_i32_e32 v5, 31, v4
	v_lshlrev_b64 v[4:5], 11, v[4:5]
	v_lshl_add_u64 v[132:133], v[2:3], 0, v[4:5]
	v_add_u32_e32 v4, s2, v37
	v_ashrrev_i32_e32 v5, 31, v4
	v_lshlrev_b64 v[4:5], 11, v[4:5]
	v_lshl_add_u64 v[134:135], v[2:3], 0, v[4:5]
	v_add_u32_e32 v4, s2, v38
	v_ashrrev_i32_e32 v5, 31, v4
	v_lshlrev_b64 v[4:5], 11, v[4:5]
	v_lshl_add_u64 v[136:137], v[2:3], 0, v[4:5]
	s_barrier
	global_load_dwordx4 v[2:5], v[122:123], off
	global_load_dwordx4 v[6:9], v[124:125], off
	global_load_dwordx4 v[10:13], v[126:127], off
	global_load_dwordx4 v[14:17], v[128:129], off
	global_load_dwordx4 v[18:21], v[130:131], off
	global_load_dwordx4 v[22:25], v[132:133], off
	global_load_dwordx4 v[26:29], v[134:135], off
	global_load_dwordx4 v[30:33], v[136:137], off
	global_load_dwordx4 v[66:69], v[134:135], off offset:128
	global_load_dwordx4 v[70:73], v[136:137], off offset:128
	global_load_dwordx4 v[74:77], v[122:123], off offset:128
	global_load_dwordx4 v[78:81], v[124:125], off offset:128
	global_load_dwordx4 v[82:85], v[126:127], off offset:128
	global_load_dwordx4 v[86:89], v[128:129], off offset:128
	global_load_dwordx4 v[90:93], v[130:131], off offset:128
	global_load_dwordx4 v[94:97], v[132:133], off offset:128
	v_and_b32_e32 v39, 31, v34
	v_mad_u64_u32 v[138:139], s[0:1], v35, s76, v[0:1]
	v_mad_u64_u32 v[140:141], s[0:1], v36, s76, v[0:1]
	v_mad_u64_u32 v[142:143], s[0:1], v37, s76, v[0:1]
	v_mad_u64_u32 v[144:145], s[0:1], v38, s76, v[0:1]
	v_lshrrev_b32_e32 v0, 1, v34
	s_mov_b32 s0, -2
	v_readlane_b32 s17, v252, 10
	v_readlane_b32 s18, v252, 11
	v_readlane_b32 s19, v252, 12
	v_readlane_b32 s20, v252, 13
	v_readlane_b32 s21, v252, 14
	v_readlane_b32 s22, v252, 15
	v_readlane_b32 s23, v252, 16
	v_readlane_b32 s26, v252, 19
	v_readlane_b32 s27, v252, 20
	v_readlane_b32 s28, v252, 21
	v_readlane_b32 s29, v252, 22
	v_readlane_b32 s30, v252, 23
	v_readlane_b32 s31, v252, 24
	s_waitcnt vmcnt(15)
	ds_write_b128 v138, v[2:5]
	s_waitcnt vmcnt(14)
	ds_write_b128 v140, v[6:9]
	s_waitcnt vmcnt(13)
	ds_write_b128 v142, v[10:13]
	s_waitcnt vmcnt(12)
	ds_write_b128 v144, v[14:17]
	s_waitcnt vmcnt(11)
	ds_write_b128 v138, v[18:21] offset:18432
	s_waitcnt vmcnt(10)
	ds_write_b128 v140, v[22:25] offset:18432
	s_waitcnt vmcnt(9)
	ds_write_b128 v142, v[26:29] offset:18432
	s_waitcnt vmcnt(8)
	ds_write_b128 v144, v[30:33] offset:18432
	v_and_or_b32 v2, v0, s47, v39
	v_and_b32_e32 v3, 16, v0
	v_and_b32_e32 v0, 0x5f, v34
	v_mul_lo_u32 v4, v2, s76
	v_mul_u32_u24_e32 v5, 0x90, v0
	v_mov_b32_e32 v2, 0
	v_add_u32_e32 v0, v3, v4
	v_add_u32_e32 v139, v3, v5
	v_mov_b32_e32 v3, v2
	v_mov_b32_e32 v4, v2
	v_mov_b32_e32 v5, v2
	v_mov_b32_e32 v6, v2
	v_mov_b32_e32 v7, v2
	v_mov_b32_e32 v8, v2
	v_mov_b32_e32 v9, v2
	v_mov_b32_e32 v10, v2
	v_mov_b32_e32 v11, v2
	v_mov_b32_e32 v12, v2
	v_mov_b32_e32 v13, v2
	v_mov_b32_e32 v14, v2
	v_mov_b32_e32 v15, v2
	v_mov_b32_e32 v16, v2
	v_mov_b32_e32 v17, v2
	v_mov_b32_e32 v18, v2
	v_mov_b32_e32 v19, v2
	v_mov_b32_e32 v20, v2
	v_mov_b32_e32 v21, v2
	v_mov_b32_e32 v22, v2
	v_mov_b32_e32 v23, v2
	v_mov_b32_e32 v24, v2
	v_mov_b32_e32 v25, v2
	v_mov_b32_e32 v26, v2
	v_mov_b32_e32 v27, v2
	v_mov_b32_e32 v28, v2
	v_mov_b32_e32 v29, v2
	v_mov_b32_e32 v30, v2
	v_mov_b32_e32 v31, v2
	v_mov_b32_e32 v32, v2
	v_mov_b32_e32 v33, v2
	v_mov_b32_e32 v34, v2
	v_mov_b32_e32 v35, v2
	v_mov_b32_e32 v36, v2
	v_mov_b32_e32 v37, v2
	v_mov_b32_e32 v38, v2
	v_mov_b32_e32 v39, v2
	v_mov_b32_e32 v40, v2
	v_mov_b32_e32 v41, v2
	v_mov_b32_e32 v42, v2
	v_mov_b32_e32 v43, v2
	v_mov_b32_e32 v44, v2
	v_mov_b32_e32 v45, v2
	v_mov_b32_e32 v46, v2
	v_mov_b32_e32 v47, v2
	v_mov_b32_e32 v48, v2
	v_mov_b32_e32 v49, v2
	v_mov_b32_e32 v50, v2
	v_mov_b32_e32 v51, v2
	v_mov_b32_e32 v52, v2
	v_mov_b32_e32 v53, v2
	v_mov_b32_e32 v54, v2
	v_mov_b32_e32 v55, v2
	v_mov_b32_e32 v56, v2
	v_mov_b32_e32 v57, v2
	v_mov_b32_e32 v58, v2
	v_mov_b32_e32 v59, v2
	v_mov_b32_e32 v60, v2
	v_mov_b32_e32 v61, v2
	v_mov_b32_e32 v62, v2
	v_mov_b32_e32 v63, v2
	v_mov_b32_e32 v64, v2
	v_mov_b32_e32 v65, v2
	s_waitcnt lgkmcnt(0)
; #define G_STORE(ST, S, unused) do { char* d_ = smem + (ST) * STAGE; \
;     *(uint4*)(d_ + alo[0]) = S##a0; *(uint4*)(d_ + alo[1]) = S##a1; *(uint4*)(d_ + alo[2]) = S##a2; *(uint4*)(d_ + alo[3]) = S##a3; \
;     *(uint4*)(d_ + blo[0]) = S##b0; *(uint4*)(d_ + blo[1]) = S##b1; \
;     if (NBCH == 4) { *(uint4*)(d_ + blo[NBCH - 2]) = S##b2; *(uint4*)(d_ + blo[NBCH - 1]) = S##b3; } } while (0)
; template <int NJ, class RowA>
; DI void gemm_main(f32x16 (&acc)[2][NJ], const bf16_t* __restrict__ A, RowA rowA, size_t kstrideA, int m0, int Mmax,
;                   const bf16_t* __restrict__ Bt, size_t ldb, int n0, int nk, char* smem) {
;     ...
; #pragma unroll 1
;   for (int kt = 0; kt < nk; kt += 2) {
;     G_LOAD(x0, 0, (kt + 2 < nk ? kt + 2 : nk - 1));
;     G_COMPUTE(0);
;     G_STORE(1, x1, 0);
;     __syncthreads();
;     G_LOAD(x1, 0, (kt + 3 < nk ? kt + 3 : nk - 1));
;     G_COMPUTE(1);
;     G_STORE(0, x0, 0);
;     __syncthreads();
;   }
.LBB0_1956:
	s_cmp_lt_i32 s0, 12
	s_cbranch_scc0 .Lrot_exit_1956
.Lrot_body_1956:
	s_barrier
	ds_read_b128 v[166:169], v0
	ds_read_b128 v[170:173], v139 offset:18432
	ds_read_b128 v[174:177], v139 offset:23040
	ds_read_b128 v[178:181], v0 offset:4608
	s_add_i32 s1, s0, 4
	s_min_u32 s1, s1, 15
	s_lshl_b32 s14, s1, 7
	v_lshl_add_u64 v[98:99], v[122:123], 0, s[14:15]
	v_lshl_add_u64 v[102:103], v[124:125], 0, s[14:15]
	v_lshl_add_u64 v[106:107], v[126:127], 0, s[14:15]
	v_lshl_add_u64 v[110:111], v[128:129], 0, s[14:15]
	v_lshl_add_u64 v[114:115], v[130:131], 0, s[14:15]
	v_lshl_add_u64 v[118:119], v[132:133], 0, s[14:15]
	s_add_i32 s0, s0, 2
	v_lshl_add_u64 v[158:159], v[134:135], 0, s[14:15]
	v_lshl_add_u64 v[160:161], v[136:137], 0, s[14:15]
	s_setprio 1
	ds_read_b128 v[182:185], v0 offset:32
	ds_read_b128 v[186:189], v139 offset:18464
	ds_read_b128 v[190:193], v139 offset:23072
	ds_read_b128 v[194:197], v0 offset:4640
	s_waitcnt lgkmcnt(4)
	v_mfma_f32_32x32x16_bf16 v[50:65], v[166:169], v[170:173], v[50:65]
	global_load_dwordx4 v[98:101], v[98:99], off
	v_mfma_f32_32x32x16_bf16 v[34:49], v[166:169], v[174:177], v[34:49]
	global_load_dwordx4 v[102:105], v[102:103], off
	v_mfma_f32_32x32x16_bf16 v[18:33], v[178:181], v[170:173], v[18:33]
	global_load_dwordx4 v[106:109], v[106:107], off
	v_mfma_f32_32x32x16_bf16 v[2:17], v[178:181], v[174:177], v[2:17]
	global_load_dwordx4 v[110:113], v[110:111], off
	ds_read_b128 v[166:169], v0 offset:64
	ds_read_b128 v[170:173], v139 offset:18496
	ds_read_b128 v[174:177], v139 offset:23104
	ds_read_b128 v[178:181], v0 offset:4672
	s_waitcnt lgkmcnt(4)
	v_mfma_f32_32x32x16_bf16 v[50:65], v[182:185], v[186:189], v[50:65]
	global_load_dwordx4 v[114:117], v[114:115], off
	s_waitcnt vmcnt(5)
	ds_write_b128 v138, v[74:77] offset:36864
	v_mfma_f32_32x32x16_bf16 v[34:49], v[182:185], v[190:193], v[34:49]
	global_load_dwordx4 v[118:121], v[118:119], off
	ds_write_b128 v140, v[78:81] offset:36864
	v_mfma_f32_32x32x16_bf16 v[18:33], v[194:197], v[186:189], v[18:33]
	global_load_dwordx4 v[146:149], v[160:161], off
	ds_write_b128 v142, v[82:85] offset:36864
	v_mfma_f32_32x32x16_bf16 v[2:17], v[194:197], v[190:193], v[2:17]
	global_load_dwordx4 v[150:153], v[158:159], off
	ds_write_b128 v144, v[86:89] offset:36864
	ds_read_b128 v[182:185], v0 offset:96
	ds_read_b128 v[186:189], v139 offset:18528
	ds_read_b128 v[190:193], v139 offset:23136
	ds_read_b128 v[194:197], v0 offset:4704
	s_waitcnt lgkmcnt(8)
	v_mfma_f32_32x32x16_bf16 v[50:65], v[166:169], v[170:173], v[50:65]
	ds_write_b128 v138, v[90:93] offset:55296
	v_mfma_f32_32x32x16_bf16 v[34:49], v[166:169], v[174:177], v[34:49]
	ds_write_b128 v140, v[94:97] offset:55296
	v_mfma_f32_32x32x16_bf16 v[18:33], v[178:181], v[170:173], v[18:33]
	ds_write_b128 v142, v[66:69] offset:55296
	v_mfma_f32_32x32x16_bf16 v[2:17], v[178:181], v[174:177], v[2:17]
	ds_write_b128 v144, v[70:73] offset:55296
	s_waitcnt lgkmcnt(4)
	v_mfma_f32_32x32x16_bf16 v[50:65], v[182:185], v[186:189], v[50:65]
	v_mfma_f32_32x32x16_bf16 v[34:49], v[182:185], v[190:193], v[34:49]
	v_mfma_f32_32x32x16_bf16 v[18:33], v[194:197], v[186:189], v[18:33]
	v_mfma_f32_32x32x16_bf16 v[2:17], v[194:197], v[190:193], v[2:17]
	s_setprio 0
	s_min_u32 s1, s0, 12
	s_lshl_b32 s14, s1, 7
	v_lshl_add_u64 v[66:67], v[122:123], 0, s[14:15]
	v_lshl_add_u64 v[68:69], v[124:125], 0, s[14:15]
	v_lshl_add_u64 v[70:71], v[126:127], 0, s[14:15]
	v_lshl_add_u64 v[72:73], v[128:129], 0, s[14:15]
	v_lshl_add_u64 v[90:91], v[130:131], 0, s[14:15]
	v_lshl_add_u64 v[94:95], v[132:133], 0, s[14:15]
	s_waitcnt lgkmcnt(0)
	s_barrier
	ds_read_b128 v[166:169], v0 offset:36864
	ds_read_b128 v[170:173], v139 offset:55296
	ds_read_b128 v[174:177], v139 offset:59904
	ds_read_b128 v[178:181], v0 offset:41472
	v_lshl_add_u64 v[154:155], v[134:135], 0, s[14:15]
	v_lshl_add_u64 v[156:157], v[136:137], 0, s[14:15]
	s_setprio 1
	ds_read_b128 v[182:185], v0 offset:36896
	ds_read_b128 v[186:189], v139 offset:55328
	ds_read_b128 v[190:193], v139 offset:59936
	ds_read_b128 v[194:197], v0 offset:41504
	s_waitcnt lgkmcnt(4)
	v_mfma_f32_32x32x16_bf16 v[50:65], v[166:169], v[170:173], v[50:65]
	global_load_dwordx4 v[74:77], v[66:67], off offset:384
	v_mfma_f32_32x32x16_bf16 v[34:49], v[166:169], v[174:177], v[34:49]
	global_load_dwordx4 v[78:81], v[68:69], off offset:384
	v_mfma_f32_32x32x16_bf16 v[18:33], v[178:181], v[170:173], v[18:33]
	global_load_dwordx4 v[82:85], v[70:71], off offset:384
	v_mfma_f32_32x32x16_bf16 v[2:17], v[178:181], v[174:177], v[2:17]
	global_load_dwordx4 v[86:89], v[72:73], off offset:384
	ds_read_b128 v[166:169], v0 offset:36928
	ds_read_b128 v[170:173], v139 offset:55360
	ds_read_b128 v[174:177], v139 offset:59968
	ds_read_b128 v[178:181], v0 offset:41536
	s_waitcnt lgkmcnt(4)
	v_mfma_f32_32x32x16_bf16 v[50:65], v[182:185], v[186:189], v[50:65]
	global_load_dwordx4 v[90:93], v[90:91], off offset:384
	s_waitcnt vmcnt(5)
	ds_write_b128 v138, v[98:101]
	v_mfma_f32_32x32x16_bf16 v[34:49], v[182:185], v[190:193], v[34:49]
	global_load_dwordx4 v[94:97], v[94:95], off offset:384
	ds_write_b128 v140, v[102:105]
	v_mfma_f32_32x32x16_bf16 v[18:33], v[194:197], v[186:189], v[18:33]
	global_load_dwordx4 v[66:69], v[154:155], off offset:384
	ds_write_b128 v142, v[106:109]
	v_mfma_f32_32x32x16_bf16 v[2:17], v[194:197], v[190:193], v[2:17]
	global_load_dwordx4 v[70:73], v[156:157], off offset:384
	ds_write_b128 v144, v[110:113]
	ds_read_b128 v[182:185], v0 offset:36960
	ds_read_b128 v[186:189], v139 offset:55392
	ds_read_b128 v[190:193], v139 offset:60000
	ds_read_b128 v[194:197], v0 offset:41568
	s_waitcnt lgkmcnt(8)
	v_mfma_f32_32x32x16_bf16 v[50:65], v[166:169], v[170:173], v[50:65]
	ds_write_b128 v138, v[114:117] offset:18432
	v_mfma_f32_32x32x16_bf16 v[34:49], v[166:169], v[174:177], v[34:49]
	ds_write_b128 v140, v[118:121] offset:18432
	v_mfma_f32_32x32x16_bf16 v[18:33], v[178:181], v[170:173], v[18:33]
	ds_write_b128 v142, v[150:153] offset:18432
	v_mfma_f32_32x32x16_bf16 v[2:17], v[178:181], v[174:177], v[2:17]
	ds_write_b128 v144, v[146:149] offset:18432
	s_waitcnt lgkmcnt(4)
	v_mfma_f32_32x32x16_bf16 v[50:65], v[182:185], v[186:189], v[50:65]
	v_mfma_f32_32x32x16_bf16 v[34:49], v[182:185], v[190:193], v[34:49]
	v_mfma_f32_32x32x16_bf16 v[18:33], v[194:197], v[186:189], v[18:33]
	v_mfma_f32_32x32x16_bf16 v[2:17], v[194:197], v[190:193], v[2:17]
	s_setprio 0
	s_cmp_lt_u32 s0, 14
	s_waitcnt lgkmcnt(0)
	s_cmp_lt_i32 s0, 12
	s_cbranch_scc0 .Lrot_exit_1956
	s_branch .Lrot_body_1956

; #define TIDX (tid_launder())
; #define G_STORE(ST, S, unused) do { char* d_ = smem + (ST) * STAGE; \
;     *(uint4*)(d_ + alo[0]) = S##a0; *(uint4*)(d_ + alo[1]) = S##a1; *(uint4*)(d_ + alo[2]) = S##a2; *(uint4*)(d_ + alo[3]) = S##a3; \
;     *(uint4*)(d_ + blo[0]) = S##b0; *(uint4*)(d_ + blo[1]) = S##b1; \
;     if (NBCH == 4) { *(uint4*)(d_ + blo[NBCH - 2]) = S##b2; *(uint4*)(d_ + blo[NBCH - 1]) = S##b3; } } while (0)
; template <int NJ, class RowA>
; DI void gemm_main(f32x16 (&acc)[2][NJ], const bf16_t* __restrict__ A, RowA rowA, size_t kstrideA, int m0, int Mmax,
;                   const bf16_t* __restrict__ Bt, size_t ldb, int n0, int nk, char* smem) {
;     ...
;   const int tid = TIDX, lane = tid & 63, wid = tid >> 6, wm = wid >> 1, wn = wid & 1;
;   const int r = lane & 31, hh = lane >> 5;
;   const bf16_t* ap[4]; const bf16_t* bp[NBCH]; int alo[4], blo[NBCH];
; #pragma unroll
;   for (int i = 0; i < 4; ++i) {
;     const int c = tid + 256 * i, row = c >> 3, kc = c & 7;
;     int m = m0 + row; m = m < Mmax ? m : Mmax - 1;
;     ap[i] = A + rowA(m) + kc * 8; alo[i] = row * 144 + kc * 16;
;   }
; #pragma unroll
;   for (int i = 0; i < NBCH; ++i) {
;     const int c = tid + 256 * i, row = c >> 3, kc = c & 7;
;     bp[i] = Bt + (size_t)(n0 + row) * ldb + kc * 8; blo[i] = 128 * 144 + row * 144 + kc * 16;
;   }
; #pragma unroll
;   for (int i = 0; i < 2; ++i)
; #pragma unroll
;     for (int j = 0; j < NJ; ++j)
; #pragma unroll
;       for (int e = 0; e < 16; ++e) acc[i][j][e] = 0.f;
;   uint4 x0a0, x0a1, x0a2, x0a3, x0b0, x0b1, x0b2, x0b3, x1a0, x1a1, x1a2, x1a3, x1b0, x1b1, x1b2, x1b3;
;   x0b2 = x0b3 = x1b2 = x1b3 = make_uint4(0, 0, 0, 0);
;     ...
;   __syncthreads();
;   G_LOAD(x0, 0, 0);
;   G_LOAD(x1, 0, 1);
;   G_STORE(0, x0, 0);
;   __syncthreads();
; #pragma unroll 1
;   for (int kt = 0; kt < nk; kt += 2) {
; DI void phase_inproj(const Params& p, int l, bool partB, int skipb, char* smem) {
;     ...
;   for (int idx = vblk >> 3; idx < per; idx += nvb >> 3) {
;     const int t = (vblk & 7) * per + idx;
;     const int mt = t / ntn; int tn = t % ntn;
;     if (partB) tn += 12; else if (tn >= 12) tn += 13;
;     inproj_tile(p, l, mt, tn, smem);
.LBB0_2148:
	v_readlane_b32 s0, v252, 4
	s_add_i32 s0, s12, s0
	s_mul_hi_i32 s2, s0, 0x4ec4ec4f
	s_lshr_b32 s3, s2, 31
	s_ashr_i32 s1, s2, 2
	s_add_i32 s1, s1, s3
	v_mov_b32_e32 v34, v230
	s_lshl_b32 s13, s1, 7
	v_readlane_b32 s16, v252, 57
	v_ashrrev_i32_e32 v35, 3, v34
	v_add_u32_e32 v4, s13, v35
	v_lshlrev_b32_e32 v0, 4, v34
	v_min_i32_e32 v4, 0x7fff, v4
	v_and_b32_e32 v0, 0x70, v0
	v_readlane_b32 s22, v252, 63
	v_readlane_b32 s23, v253, 0
	v_ashrrev_i32_e32 v5, 31, v4
	v_lshlrev_b64 v[4:5], 11, v[4:5]
	v_lshl_add_u64 v[2:3], s[22:23], 0, v[0:1]
	v_lshl_add_u64 v[122:123], v[2:3], 0, v[4:5]
	v_add_u32_e32 v4, 0x100, v34
	v_ashrrev_i32_e32 v36, 3, v4
	v_add_u32_e32 v4, s13, v36
	v_min_i32_e32 v4, 0x7fff, v4
	v_ashrrev_i32_e32 v5, 31, v4
	v_lshlrev_b64 v[4:5], 11, v[4:5]
	v_lshl_add_u64 v[124:125], v[2:3], 0, v[4:5]
	v_add_u32_e32 v4, 0x200, v34
	v_ashrrev_i32_e32 v37, 3, v4
	v_add_u32_e32 v4, s13, v37
	v_min_i32_e32 v4, 0x7fff, v4
	v_ashrrev_i32_e32 v5, 31, v4
	v_lshlrev_b64 v[4:5], 11, v[4:5]
	v_lshl_add_u64 v[126:127], v[2:3], 0, v[4:5]
	v_add_u32_e32 v4, 0x300, v34
	v_ashrrev_i32_e32 v38, 3, v4
	s_mul_i32 s4, s1, 13
	v_add_u32_e32 v4, s13, v38
	s_sub_i32 s68, s0, s4
	v_min_i32_e32 v4, 0x7fff, v4
	s_add_i32 s35, s68, 12
	v_ashrrev_i32_e32 v5, 31, v4
	s_lshl_b32 s34, s35, 7
	v_readlane_b32 s17, v252, 58
	v_readlane_b32 s18, v252, 59
	v_readlane_b32 s19, v252, 60
	v_readlane_b32 s20, v252, 61
	v_readlane_b32 s21, v252, 62
	v_readlane_b32 s24, v253, 1
	v_readlane_b32 s25, v253, 2
	v_readlane_b32 s26, v253, 3
	v_readlane_b32 s27, v253, 4
	v_readlane_b32 s28, v253, 5
	v_readlane_b32 s29, v253, 6
	v_readlane_b32 s30, v253, 7
	v_readlane_b32 s31, v253, 8
	v_lshlrev_b64 v[4:5], 11, v[4:5]
	v_lshl_add_u64 v[128:129], v[2:3], 0, v[4:5]
	v_readlane_b32 s16, v252, 9
	v_add_u32_e32 v4, s34, v35
	v_readlane_b32 s24, v252, 17
	v_readlane_b32 s25, v252, 18
	v_ashrrev_i32_e32 v5, 31, v4
	v_lshlrev_b64 v[4:5], 11, v[4:5]
	v_lshl_add_u64 v[2:3], s[24:25], 0, v[0:1]
	v_lshl_add_u64 v[130:131], v[2:3], 0, v[4:5]
	v_add_u32_e32 v4, s34, v36
	v_ashrrev_i32_e32 v5, 31, v4
	v_lshlrev_b64 v[4:5], 11, v[4:5]
	v_lshl_add_u64 v[132:133], v[2:3], 0, v[4:5]
	v_add_u32_e32 v4, s34, v37
	v_ashrrev_i32_e32 v5, 31, v4
	v_lshlrev_b64 v[4:5], 11, v[4:5]
	v_lshl_add_u64 v[134:135], v[2:3], 0, v[4:5]
	v_add_u32_e32 v4, s34, v38
	v_ashrrev_i32_e32 v5, 31, v4
	v_lshlrev_b64 v[4:5], 11, v[4:5]
	v_lshl_add_u64 v[136:137], v[2:3], 0, v[4:5]
	s_barrier
	global_load_dwordx4 v[2:5], v[122:123], off
	global_load_dwordx4 v[6:9], v[124:125], off
	global_load_dwordx4 v[10:13], v[126:127], off
	global_load_dwordx4 v[14:17], v[128:129], off
	global_load_dwordx4 v[18:21], v[130:131], off
	global_load_dwordx4 v[22:25], v[132:133], off
	global_load_dwordx4 v[26:29], v[134:135], off
	global_load_dwordx4 v[30:33], v[136:137], off
	global_load_dwordx4 v[74:77], v[122:123], off offset:128
	global_load_dwordx4 v[78:81], v[124:125], off offset:128
	global_load_dwordx4 v[82:85], v[126:127], off offset:128
	global_load_dwordx4 v[86:89], v[128:129], off offset:128
	global_load_dwordx4 v[66:69], v[134:135], off offset:128
	global_load_dwordx4 v[70:73], v[136:137], off offset:128
	global_load_dwordx4 v[90:93], v[130:131], off offset:128
	global_load_dwordx4 v[94:97], v[132:133], off offset:128
	v_and_b32_e32 v39, 31, v34
	v_mad_u64_u32 v[138:139], s[0:1], v35, s76, v[0:1]
	v_mad_u64_u32 v[140:141], s[0:1], v36, s76, v[0:1]
	v_mad_u64_u32 v[142:143], s[0:1], v37, s76, v[0:1]
	v_mad_u64_u32 v[144:145], s[0:1], v38, s76, v[0:1]
	v_lshrrev_b32_e32 v0, 1, v34
	s_mov_b32 s0, -2
	v_readlane_b32 s17, v252, 10
	v_readlane_b32 s18, v252, 11
	v_readlane_b32 s19, v252, 12
	v_readlane_b32 s20, v252, 13
	v_readlane_b32 s21, v252, 14
	v_readlane_b32 s22, v252, 15
	v_readlane_b32 s23, v252, 16
	v_readlane_b32 s26, v252, 19
	v_readlane_b32 s27, v252, 20
	v_readlane_b32 s28, v252, 21
	v_readlane_b32 s29, v252, 22
	v_readlane_b32 s30, v252, 23
	v_readlane_b32 s31, v252, 24
	s_waitcnt vmcnt(15)
	ds_write_b128 v138, v[2:5]
	s_waitcnt vmcnt(14)
	ds_write_b128 v140, v[6:9]
	s_waitcnt vmcnt(13)
	ds_write_b128 v142, v[10:13]
	s_waitcnt vmcnt(12)
	ds_write_b128 v144, v[14:17]
	s_waitcnt vmcnt(11)
	ds_write_b128 v138, v[18:21] offset:18432
	s_waitcnt vmcnt(10)
	ds_write_b128 v140, v[22:25] offset:18432
	s_waitcnt vmcnt(9)
	ds_write_b128 v142, v[26:29] offset:18432
	s_waitcnt vmcnt(8)
	ds_write_b128 v144, v[30:33] offset:18432
	v_and_or_b32 v2, v0, s47, v39
	v_and_b32_e32 v3, 16, v0
	v_and_b32_e32 v0, 0x5f, v34
	v_mul_lo_u32 v4, v2, s76
	v_mul_u32_u24_e32 v5, 0x90, v0
	v_mov_b32_e32 v2, 0
	v_add_u32_e32 v0, v3, v4
	v_add_u32_e32 v139, v3, v5
	v_mov_b32_e32 v3, v2
	v_mov_b32_e32 v4, v2
	v_mov_b32_e32 v5, v2
	v_mov_b32_e32 v6, v2
	v_mov_b32_e32 v7, v2
	v_mov_b32_e32 v8, v2
	v_mov_b32_e32 v9, v2
	v_mov_b32_e32 v10, v2
	v_mov_b32_e32 v11, v2
	v_mov_b32_e32 v12, v2
	v_mov_b32_e32 v13, v2
	v_mov_b32_e32 v14, v2
	v_mov_b32_e32 v15, v2
	v_mov_b32_e32 v16, v2
	v_mov_b32_e32 v17, v2
	v_mov_b32_e32 v18, v2
	v_mov_b32_e32 v19, v2
	v_mov_b32_e32 v20, v2
	v_mov_b32_e32 v21, v2
	v_mov_b32_e32 v22, v2
	v_mov_b32_e32 v23, v2
	v_mov_b32_e32 v24, v2
	v_mov_b32_e32 v25, v2
	v_mov_b32_e32 v26, v2
	v_mov_b32_e32 v27, v2
	v_mov_b32_e32 v28, v2
	v_mov_b32_e32 v29, v2
	v_mov_b32_e32 v30, v2
	v_mov_b32_e32 v31, v2
	v_mov_b32_e32 v32, v2
	v_mov_b32_e32 v33, v2
	v_mov_b32_e32 v34, v2
	v_mov_b32_e32 v35, v2
	v_mov_b32_e32 v36, v2
	v_mov_b32_e32 v37, v2
	v_mov_b32_e32 v38, v2
	v_mov_b32_e32 v39, v2
	v_mov_b32_e32 v40, v2
	v_mov_b32_e32 v41, v2
	v_mov_b32_e32 v42, v2
	v_mov_b32_e32 v43, v2
	v_mov_b32_e32 v44, v2
	v_mov_b32_e32 v45, v2
	v_mov_b32_e32 v46, v2
	v_mov_b32_e32 v47, v2
	v_mov_b32_e32 v48, v2
	v_mov_b32_e32 v49, v2
	v_mov_b32_e32 v50, v2
	v_mov_b32_e32 v51, v2
	v_mov_b32_e32 v52, v2
	v_mov_b32_e32 v53, v2
	v_mov_b32_e32 v54, v2
	v_mov_b32_e32 v55, v2
	v_mov_b32_e32 v56, v2
	v_mov_b32_e32 v57, v2
	v_mov_b32_e32 v58, v2
	v_mov_b32_e32 v59, v2
	v_mov_b32_e32 v60, v2
	v_mov_b32_e32 v61, v2
	v_mov_b32_e32 v62, v2
	v_mov_b32_e32 v63, v2
	v_mov_b32_e32 v64, v2
	v_mov_b32_e32 v65, v2
	s_waitcnt lgkmcnt(0)
.LBB0_2149:
	s_cmp_lt_i32 s0, 12
	s_cbranch_scc0 .Lrot_exit_2149
